# U-sweep software-pipelined by one batch: next batch MFMAs issue between the VALU reduction steps, refill loads fill DPP wait states
# speedup vs baseline: 1.0132x; 1.0019x over previous
.LBB0_88:
	s_andn2_saveexec_b64 s[0:1], s[0:1]
	v_mov_b32_e32 v22, s53
	v_add_f32_e32 v22, s49, v22
	v_add_f32_e32 v34, s52, v22
	s_or_b64 exec, exec, s[0:1]
	v_add_u32_e32 v35, 0x3000, v21
	v_max_f32_e64 v21, s48, s48
	v_max_f32_e64 v22, s44, s44
	v_max_f32_e32 v21, v22, v21
	v_max_f32_e64 v22, s45, s45
	v_max_f32_e64 v23, s95, s95
	v_max_f32_e32 v22, v23, v22
	s_mov_b32 s12, 0x1e3ce508
	v_max3_f32 v21, v21, v22, s12
	s_mov_b32 s13, 0x43700000
	v_div_scale_f32 v22, s[0:1], v21, v21, s13
	v_rcp_f32_e32 v23, v22
	v_readlane_b32 s0, v254, 10
	v_add_u32_e32 v20, 0x3000, v20
	v_readlane_b32 s1, v254, 11
	v_fma_f32 v55, -v22, v23, 1.0
	v_fmac_f32_e32 v23, v55, v23
	v_div_scale_f32 v55, vcc, s13, v21, s13
	v_mul_f32_e32 v128, v55, v23
	v_fma_f32 v187, -v22, v128, v55
	v_fmac_f32_e32 v128, v187, v23
	v_fma_f32 v22, -v22, v128, v55
	v_div_fmas_f32 v22, v22, v23, v128
	v_div_fixup_f32 v22, v22, v21, s13
	v_mul_f32_e32 v128, 0x3b888889, v21
	v_mul_f32_e32 v21, v22, v94
	v_mul_f32_e32 v23, v22, v186
	v_mov_b32_e32 v94, v155
	v_cvt_pk_fp8_f32 v94, v21, v23
	v_mul_f32_e32 v21, v22, v184
	v_mul_f32_e32 v23, v22, v185
	v_cmp_ne_u32_e32 vcc, -1, v20
	v_cvt_pk_fp8_f32 v94, v21, v23 op_sel:[0,0,1]
	v_mul_f32_e32 v21, v22, v95
	v_mul_f32_e32 v23, v22, v175
	v_mov_b32_e32 v95, v155
	v_cvt_pk_fp8_f32 v95, v21, v23
	v_mul_f32_e32 v21, v22, v173
	v_mul_f32_e32 v23, v22, v174
	v_max_f32_e64 v55, s60, s60
	v_cvt_pk_fp8_f32 v95, v21, v23 op_sel:[0,0,1]
	v_mul_f32_e32 v21, v22, v96
	v_mul_f32_e32 v23, v22, v170
	v_mov_b32_e32 v96, v155
	v_cvt_pk_fp8_f32 v96, v21, v23
	v_mul_f32_e32 v21, v22, v171
	v_mul_f32_e32 v23, v22, v172
	s_mov_b32 s95, 0
	v_cvt_pk_fp8_f32 v96, v21, v23 op_sel:[0,0,1]
	v_mul_f32_e32 v21, v22, v97
	v_mul_f32_e32 v23, v22, v169
	v_mov_b32_e32 v97, v155
	v_cvt_pk_fp8_f32 v97, v21, v23
	v_mul_f32_e32 v21, v22, v37
	v_mul_f32_e32 v22, v22, v129
	v_max_f32_e64 v37, s72, s72
	v_cvt_pk_fp8_f32 v97, v21, v22 op_sel:[0,0,1]
	v_mov_b32_e32 v21, s1
	v_cndmask_b32_e32 v23, 0, v21, vcc
	v_cndmask_b32_e32 v22, 0, v20, vcc
	v_cmp_ne_u32_e32 vcc, -1, v35
	s_nop 1
	v_cndmask_b32_e32 v20, 0, v35, vcc
	v_max_f32_e64 v35, s94, s94
	v_max_f32_e32 v35, v37, v35
	v_max_f32_e64 v37, s73, s73
	v_max_f32_e32 v37, v55, v37
	v_max3_f32 v35, v35, v37, s12
	v_div_scale_f32 v37, s[0:1], v35, v35, s13
	v_rcp_f32_e32 v55, v37
	v_cndmask_b32_e32 v21, 0, v21, vcc
	v_fma_f32 v129, -v37, v55, 1.0
	v_fmac_f32_e32 v55, v129, v55
	v_div_scale_f32 v129, vcc, s13, v35, s13
	v_mul_f32_e32 v169, v129, v55
	v_fma_f32 v170, -v37, v169, v129
	v_fmac_f32_e32 v169, v170, v55
	v_fma_f32 v37, -v37, v169, v129
	v_div_fmas_f32 v37, v37, v55, v169
	v_div_fixup_f32 v37, v37, v35, s13
	v_mul_f32_e32 v129, 0x3b888889, v35
	v_mul_f32_e32 v35, v37, v98
	v_mul_f32_e32 v55, v37, v168
	v_mov_b32_e32 v98, v155
	v_cvt_pk_fp8_f32 v98, v35, v55
	v_mul_f32_e32 v35, v37, v99
	v_mul_f32_e32 v55, v37, v163
	v_mov_b32_e32 v99, v155
	v_cvt_pk_fp8_f32 v98, v35, v55 op_sel:[0,0,1]
	v_mul_f32_e32 v35, v37, v164
	v_mul_f32_e32 v55, v37, v165
	v_cvt_pk_fp8_f32 v99, v35, v55
	v_mul_f32_e32 v35, v37, v166
	v_mul_f32_e32 v55, v37, v167
	v_cvt_pk_fp8_f32 v99, v35, v55 op_sel:[0,0,1]
	v_mul_f32_e32 v35, v37, v100
	v_mul_f32_e32 v55, v37, v162
	v_mov_b32_e32 v100, v155
	v_cvt_pk_fp8_f32 v100, v35, v55
	v_mul_f32_e32 v35, v37, v101
	v_mul_f32_e32 v55, v37, v136
	v_mov_b32_e32 v101, v155
	v_cvt_pk_fp8_f32 v100, v35, v55 op_sel:[0,0,1]
	v_mul_f32_e32 v35, v37, v153
	v_mul_f32_e32 v55, v37, v154
	v_cvt_pk_fp8_f32 v101, v35, v55
	v_mul_f32_e32 v35, v37, v160
	v_mul_f32_e32 v37, v37, v161
	v_max_f32_e64 v55, s17, s17
	v_cvt_pk_fp8_f32 v101, v35, v37 op_sel:[0,0,1]
	v_max_f32_e64 v35, s19, s19
	v_max_f32_e64 v37, s75, s75
	v_max_f32_e32 v35, v37, v35
	v_max_f32_e64 v37, s18, s18
	v_max_f32_e32 v37, v55, v37
	v_max3_f32 v35, v35, v37, s12
	v_div_scale_f32 v37, s[0:1], v35, v35, s13
	v_rcp_f32_e32 v55, v37
	s_nop 0
	v_fma_f32 v136, -v37, v55, 1.0
	v_fmac_f32_e32 v55, v136, v55
	v_div_scale_f32 v136, vcc, s13, v35, s13
	v_mul_f32_e32 v153, v136, v55
	v_fma_f32 v154, -v37, v153, v136
	v_fmac_f32_e32 v153, v154, v55
	v_fma_f32 v37, -v37, v153, v136
	v_div_fmas_f32 v37, v37, v55, v153
	v_div_fixup_f32 v37, v37, v35, s13
	v_mul_f32_e32 v136, 0x3b888889, v35
	v_mul_f32_e32 v35, v37, v102
	v_mul_f32_e32 v55, v37, v152
	v_mov_b32_e32 v102, v155
	v_cvt_pk_fp8_f32 v102, v35, v55
	v_mul_f32_e32 v35, v37, v103
	v_mul_f32_e32 v55, v37, v147
	v_mov_b32_e32 v103, v155
	v_cvt_pk_fp8_f32 v102, v35, v55 op_sel:[0,0,1]
	v_mul_f32_e32 v35, v37, v148
	v_mul_f32_e32 v55, v37, v149
	v_cvt_pk_fp8_f32 v103, v35, v55
	v_mul_f32_e32 v35, v37, v150
	v_mul_f32_e32 v55, v37, v151
	v_cvt_pk_fp8_f32 v103, v35, v55 op_sel:[0,0,1]
	v_mul_f32_e32 v35, v37, v104
	v_mul_f32_e32 v55, v37, v146
	v_mov_b32_e32 v104, v155
	v_cvt_pk_fp8_f32 v104, v35, v55
	v_mul_f32_e32 v35, v37, v105
	v_mul_f32_e32 v55, v37, v137
	v_mov_b32_e32 v105, v155
	v_cvt_pk_fp8_f32 v104, v35, v55 op_sel:[0,0,1]
	v_mul_f32_e32 v35, v37, v142
	v_mul_f32_e32 v55, v37, v143
	v_cvt_pk_fp8_f32 v105, v35, v55
	v_mul_f32_e32 v35, v37, v144
	v_mul_f32_e32 v37, v37, v145
	v_max_f32_e64 v55, s31, s31
	v_cvt_pk_fp8_f32 v105, v35, v37 op_sel:[0,0,1]
	v_max_f32_e64 v35, s16, s16
	v_max_f32_e64 v37, s10, s10
	v_max_f32_e32 v35, v37, v35
	v_max_f32_e64 v37, s11, s11
	v_max_f32_e32 v37, v55, v37
	v_max3_f32 v35, v35, v37, s12
	v_div_scale_f32 v37, s[0:1], v35, v35, s13
	v_rcp_f32_e32 v55, v37
	s_bfe_i32 s10, s96, 0x10000
	v_fma_f32 v137, -v37, v55, 1.0
	v_fmac_f32_e32 v55, v137, v55
	v_div_scale_f32 v137, vcc, s13, v35, s13
	v_mul_f32_e32 v142, v137, v55
	v_fma_f32 v143, -v37, v142, v137
	v_fmac_f32_e32 v142, v143, v55
	v_fma_f32 v37, -v37, v142, v137
	v_div_fmas_f32 v37, v37, v55, v142
	v_div_fixup_f32 v37, v37, v35, s13
	v_mul_f32_e32 v137, 0x3b888889, v35
	v_mul_f32_e32 v35, v37, v106
	v_mul_f32_e32 v55, v37, v141
	v_mov_b32_e32 v106, v155
	v_cvt_pk_fp8_f32 v106, v35, v55
	v_mul_f32_e32 v35, v37, v107
	v_mul_f32_e32 v55, v37, v126
	v_mov_b32_e32 v107, v155
	v_cvt_pk_fp8_f32 v106, v35, v55 op_sel:[0,0,1]
	v_mul_f32_e32 v35, v37, v127
	v_mul_f32_e32 v55, v37, v138
	v_cvt_pk_fp8_f32 v107, v35, v55
	v_mul_f32_e32 v35, v37, v139
	v_mul_f32_e32 v55, v37, v140
	v_cvt_pk_fp8_f32 v107, v35, v55 op_sel:[0,0,1]
	v_mul_f32_e32 v35, v37, v108
	v_mul_f32_e32 v55, v37, v125
	v_mov_b32_e32 v108, v155
	v_cvt_pk_fp8_f32 v108, v35, v55
	v_mul_f32_e32 v35, v37, v109
	v_mul_f32_e32 v55, v37, v120
	v_mov_b32_e32 v109, v155
	v_cvt_pk_fp8_f32 v108, v35, v55 op_sel:[0,0,1]
	v_mul_f32_e32 v35, v37, v121
	v_mul_f32_e32 v55, v37, v122
	v_cvt_pk_fp8_f32 v109, v35, v55
	v_mul_f32_e32 v35, v37, v123
	v_mul_f32_e32 v37, v37, v124
	v_max_f32_e64 v55, s97, s97
	v_cvt_pk_fp8_f32 v109, v35, v37 op_sel:[0,0,1]
	v_max_f32_e64 v35, s30, s30
	v_max_f32_e64 v37, s20, s20
	v_max_f32_e32 v35, v37, v35
	v_max_f32_e64 v37, s21, s21
	v_max_f32_e32 v37, v55, v37
	v_max3_f32 v35, v35, v37, s12
	v_div_scale_f32 v37, s[0:1], v35, v35, s13
	v_rcp_f32_e32 v55, v37
	v_mul_f32_e32 v138, 0x3b888889, v35
	v_mov_b32_e32 v123, v155
	v_mov_b32_e32 v124, v155
	v_fma_f32 v120, -v37, v55, 1.0
	v_fmac_f32_e32 v55, v120, v55
	v_div_scale_f32 v120, vcc, s13, v35, s13
	v_mul_f32_e32 v121, v120, v55
	v_fma_f32 v122, -v37, v121, v120
	v_fmac_f32_e32 v121, v122, v55
	v_fma_f32 v37, -v37, v121, v120
	v_div_fmas_f32 v37, v37, v55, v121
	v_div_fixup_f32 v37, v37, v35, s13
	v_mul_f32_e32 v35, v37, v110
	v_mul_f32_e32 v55, v37, v119
	v_mov_b32_e32 v110, v155
	v_cvt_pk_fp8_f32 v110, v35, v55
	v_mul_f32_e32 v35, v37, v111
	v_mul_f32_e32 v55, v37, v114
	v_mov_b32_e32 v111, v155
	v_cvt_pk_fp8_f32 v110, v35, v55 op_sel:[0,0,1]
	v_mul_f32_e32 v35, v37, v115
	v_mul_f32_e32 v55, v37, v116
	v_cvt_pk_fp8_f32 v111, v35, v55
	v_mul_f32_e32 v35, v37, v117
	v_mul_f32_e32 v55, v37, v118
	v_mov_b32_e32 v114, v155
	v_cvt_pk_fp8_f32 v111, v35, v55 op_sel:[0,0,1]
	v_mul_f32_e32 v35, v37, v112
	v_mul_f32_e32 v55, v37, v113
	v_mov_b32_e32 v112, v155
	v_cvt_pk_fp8_f32 v112, v35, v55
	v_mul_f32_e32 v35, v37, v88
	v_mul_f32_e32 v55, v37, v89
	v_mov_b32_e32 v113, v155
	v_cvt_pk_fp8_f32 v112, v35, v55 op_sel:[0,0,1]
	v_mul_f32_e32 v35, v37, v90
	v_mul_f32_e32 v55, v37, v91
	v_cvt_pk_fp8_f32 v113, v35, v55
	v_mul_f32_e32 v35, v37, v92
	v_mul_f32_e32 v37, v37, v93
	v_max_f32_e64 v55, s90, s90
	v_cvt_pk_fp8_f32 v113, v35, v37 op_sel:[0,0,1]
	v_max_f32_e64 v35, s92, s92
	v_max_f32_e64 v37, s74, s74
	v_max_f32_e32 v35, v37, v35
	v_max_f32_e64 v37, s91, s91
	v_max_f32_e32 v37, v55, v37
	v_max3_f32 v35, v35, v37, s12
	v_div_scale_f32 v37, s[0:1], v35, v35, s13
	v_rcp_f32_e32 v55, v37
	v_mul_f32_e32 v139, 0x3b888889, v35
	v_mov_b32_e32 v115, v155
	v_mov_b32_e32 v116, v155
	v_fma_f32 v88, -v37, v55, 1.0
	v_fmac_f32_e32 v55, v88, v55
	v_div_scale_f32 v88, vcc, s13, v35, s13
	v_mul_f32_e32 v89, v88, v55
	v_fma_f32 v90, -v37, v89, v88
	v_fmac_f32_e32 v89, v90, v55
	v_fma_f32 v37, -v37, v89, v88
	v_div_fmas_f32 v37, v37, v55, v89
	v_div_fixup_f32 v37, v37, v35, s13
	v_mul_f32_e32 v35, v37, v80
	v_mul_f32_e32 v55, v37, v81
	v_cvt_pk_fp8_f32 v114, v35, v55
	v_mul_f32_e32 v35, v37, v82
	v_mul_f32_e32 v55, v37, v83
	v_mov_b32_e32 v117, v155
	v_cvt_pk_fp8_f32 v114, v35, v55 op_sel:[0,0,1]
	v_mul_f32_e32 v35, v37, v84
	v_mul_f32_e32 v55, v37, v85
	v_cvt_pk_fp8_f32 v115, v35, v55
	v_mul_f32_e32 v35, v37, v86
	v_mul_f32_e32 v55, v37, v87
	v_readlane_b32 s0, v254, 44
	v_cvt_pk_fp8_f32 v115, v35, v55 op_sel:[0,0,1]
	v_mul_f32_e32 v35, v37, v72
	v_mul_f32_e32 v55, v37, v73
	v_cvt_pk_fp8_f32 v116, v35, v55
	v_mul_f32_e32 v35, v37, v74
	v_mul_f32_e32 v55, v37, v75
	v_mov_b32_e32 v118, v155
	v_cvt_pk_fp8_f32 v116, v35, v55 op_sel:[0,0,1]
	v_mul_f32_e32 v35, v37, v76
	v_mul_f32_e32 v55, v37, v77
	v_cvt_pk_fp8_f32 v117, v35, v55
	v_mul_f32_e32 v35, v37, v78
	v_mul_f32_e32 v37, v37, v79
	v_max_f32_e64 v55, s0, s0
	v_cvt_pk_fp8_f32 v117, v35, v37 op_sel:[0,0,1]
	v_max_f32_e64 v35, s37, s37
	v_max_f32_e64 v37, s35, s35
	v_max_f32_e32 v35, v37, v35
	v_max_f32_e64 v37, s36, s36
	v_max_f32_e32 v37, v55, v37
	v_max3_f32 v35, v35, v37, s12
	v_div_scale_f32 v37, s[0:1], v35, v35, s13
	v_rcp_f32_e32 v55, v37
	v_mul_f32_e32 v140, 0x3b888889, v35
	v_mov_b32_e32 v119, v155
	v_mov_b32_e32 v120, v155
	v_fma_f32 v72, -v37, v55, 1.0
	v_fmac_f32_e32 v55, v72, v55
	v_div_scale_f32 v72, vcc, s13, v35, s13
	v_mul_f32_e32 v73, v72, v55
	v_fma_f32 v74, -v37, v73, v72
	v_fmac_f32_e32 v73, v74, v55
	v_fma_f32 v37, -v37, v73, v72
	v_div_fmas_f32 v37, v37, v55, v73
	v_div_fixup_f32 v37, v37, v35, s13
	v_mul_f32_e32 v35, v37, v64
	v_mul_f32_e32 v55, v37, v65
	v_cvt_pk_fp8_f32 v118, v35, v55
	v_mul_f32_e32 v35, v37, v66
	v_mul_f32_e32 v55, v37, v67
	v_mov_b32_e32 v121, v155
	v_cvt_pk_fp8_f32 v118, v35, v55 op_sel:[0,0,1]
	v_mul_f32_e32 v35, v37, v68
	v_mul_f32_e32 v55, v37, v69
	v_cvt_pk_fp8_f32 v119, v35, v55
	v_mul_f32_e32 v35, v37, v70
	v_mul_f32_e32 v55, v37, v71
	v_readlane_b32 s0, v254, 42
	v_cvt_pk_fp8_f32 v119, v35, v55 op_sel:[0,0,1]
	v_mul_f32_e32 v35, v37, v56
	v_mul_f32_e32 v55, v37, v57
	v_cvt_pk_fp8_f32 v120, v35, v55
	v_mul_f32_e32 v35, v37, v58
	v_mul_f32_e32 v55, v37, v59
	v_mov_b32_e32 v122, v155
	v_cvt_pk_fp8_f32 v120, v35, v55 op_sel:[0,0,1]
	v_mul_f32_e32 v35, v37, v60
	v_mul_f32_e32 v55, v37, v61
	v_cvt_pk_fp8_f32 v121, v35, v55
	v_mul_f32_e32 v35, v37, v62
	v_mul_f32_e32 v37, v37, v63
	v_mov_b32_e32 v125, v155
	v_cvt_pk_fp8_f32 v121, v35, v37 op_sel:[0,0,1]
	v_max_f32_e64 v35, s0, s0
	v_readlane_b32 s0, v254, 38
	s_mov_b32 s36, 30
	s_nop 0
	v_max_f32_e64 v37, s0, s0
	v_readlane_b32 s0, v254, 40
	v_max_f32_e32 v35, v37, v35
	s_nop 0
	v_max_f32_e64 v37, s0, s0
	v_readlane_b32 s0, v254, 36
	s_nop 1
	v_max_f32_e64 v55, s0, s0
	v_max_f32_e32 v37, v55, v37
	v_max3_f32 v35, v35, v37, s12
	v_div_scale_f32 v37, s[0:1], v35, v35, s13
	v_rcp_f32_e32 v55, v37
	v_mul_f32_e32 v141, 0x3b888889, v35
	s_and_b32 s0, s96, 1
	s_cmp_eq_u32 s0, 0
	v_fma_f32 v56, -v37, v55, 1.0
	v_fmac_f32_e32 v55, v56, v55
	v_div_scale_f32 v56, vcc, s13, v35, s13
	v_mul_f32_e32 v57, v56, v55
	v_fma_f32 v58, -v37, v57, v56
	v_fmac_f32_e32 v57, v58, v55
	v_fma_f32 v37, -v37, v57, v56
	v_div_fmas_f32 v37, v37, v55, v57
	v_div_fixup_f32 v37, v37, v35, s13
	v_mul_f32_e32 v35, v37, v47
	v_mul_f32_e32 v47, v37, v48
	v_cvt_pk_fp8_f32 v122, v35, v47
	v_mul_f32_e32 v35, v37, v49
	v_mul_f32_e32 v47, v37, v50
	v_mul_f32_e32 v1, v37, v1
	v_cvt_pk_fp8_f32 v122, v35, v47 op_sel:[0,0,1]
	v_mul_f32_e32 v35, v37, v51
	v_mul_f32_e32 v47, v37, v52
	v_cvt_pk_fp8_f32 v123, v35, v47
	v_mul_f32_e32 v35, v37, v53
	v_mul_f32_e32 v47, v37, v54
	s_cselect_b64 s[0:1], -1, 0
	v_cvt_pk_fp8_f32 v123, v35, v47 op_sel:[0,0,1]
	v_mul_f32_e32 v35, v37, v40
	v_cvt_pk_fp8_f32 v124, v1, v35
	v_mul_f32_e32 v1, v37, v41
	v_mul_f32_e32 v35, v37, v42
	s_and_b32 s34, s10, 31
	v_cvt_pk_fp8_f32 v124, v1, v35 op_sel:[0,0,1]
	v_mul_f32_e32 v1, v37, v43
	v_mul_f32_e32 v35, v37, v44
	v_cvt_pk_fp8_f32 v125, v1, v35
	v_mul_f32_e32 v1, v37, v45
	v_mul_f32_e32 v35, v37, v46
	v_ashrrev_i32_e32 v37, 31, v36
	v_cvt_pk_fp8_f32 v125, v1, v35 op_sel:[0,0,1]
	v_add_f32_e32 v1, v33, v34
	v_cvt_u32_f32_e32 v1, v1
	s_lshl_b32 s35, s34, 4
	s_add_i32 s10, s93, s35
	v_mov_b32_e32 v62, s10
	v_sub_u32_e32 v1, v1, v32
	flat_store_dword v[2:3], v1 sc0 sc1
	s_waitcnt vmcnt(0)
	v_add_u32_e32 v1, v1, v26
	flat_store_dword v[4:5], v1 sc0 sc1
	s_waitcnt vmcnt(0)
	v_add_u32_e32 v1, v1, v25
	flat_store_dword v[6:7], v1 sc0 sc1
	s_waitcnt vmcnt(0)
	v_add_u32_e32 v1, v1, v28
	flat_store_dword v[8:9], v1 sc0 sc1
	s_waitcnt vmcnt(0)
	v_add_u32_e32 v1, v1, v27
	flat_store_dword v[10:11], v1 sc0 sc1
	s_waitcnt vmcnt(0)
	v_add_u32_e32 v1, v1, v30
	flat_store_dword v[12:13], v1 sc0 sc1
	s_waitcnt vmcnt(0)
	v_add_u32_e32 v1, v1, v29
	flat_store_dword v[14:15], v1 sc0 sc1
	s_waitcnt vmcnt(0)
	v_add_u32_e32 v1, v1, v31
	flat_store_dword v[16:17], v1 sc0 sc1
	s_waitcnt vmcnt(0)
	s_waitcnt lgkmcnt(0)
	flat_load_dword v1, v[22:23] sc0 sc1
	s_waitcnt vmcnt(0)
	flat_load_dword v2, v[20:21] sc0 sc1
	s_waitcnt vmcnt(0)
	s_waitcnt lgkmcnt(0)
	v_lshl_add_u64 v[4:5], v[36:37], 3, s[28:29]
	global_load_dwordx2 v[4:5], v[4:5], off
	s_waitcnt lgkmcnt(0)
	v_add_u32_e32 v1, v1, v19
	v_ashrrev_i32_e32 v19, 31, v18
	v_add_u32_e32 v6, v2, v24
	v_lshl_add_u64 v[2:3], v[18:19], 3, s[28:29]
	global_load_dwordx2 v[2:3], v[2:3], off
	v_lshl_add_u32 v1, v1, 2, s93
	s_waitcnt vmcnt(0)
	v_mul_f32_e32 v3, v38, v3
	ds_write2st64_b32 v1, v18, v3 offset0:42 offset1:44
	ds_write_b32 v1, v2 offset:11776
	v_lshl_add_u32 v1, v6, 2, s93
	v_mul_f32_e32 v2, v39, v5
	ds_write2st64_b32 v1, v36, v2 offset0:42 offset1:44
	ds_write_b32 v1, v4 offset:11776
	s_waitcnt lgkmcnt(0)
	v_readfirstlane_b32 s98, v130
	v_readfirstlane_b32 s99, v131
	v_lshlrev_b32_e32 v92, 4, v176
	s_mov_b32 s95, 0
	s_cmp_lg_u64 s[0:1], 0
	s_cselect_b32 s34, 0, 31
	s_lshl_b32 s36, s34, 4
	v_add_u32_e32 v89, s36, v181
	s_add_i32 s10, s93, s36
	v_mov_b32_e32 v91, s10
	ds_read_b128 v[66:69], v91 offset:0
	ds_read_b128 v[70:73], v91 offset:1536
	ds_read_b128 v[74:77], v91 offset:3072
	ds_read_b128 v[78:81], v91 offset:4608
	s_waitcnt lgkmcnt(3)
	v_lshl_add_u32 v145, v66, 10, v92
	global_load_dwordx4 v[2:5], v145, s[98:99]
	v_lshl_add_u32 v147, v67, 10, v92
	global_load_dwordx4 v[6:9], v147, s[98:99]
	v_lshl_add_u32 v145, v68, 10, v92
	global_load_dwordx4 v[10:13], v145, s[98:99]
	v_lshl_add_u32 v147, v69, 10, v92
	global_load_dwordx4 v[14:17], v147, s[98:99]
	ds_read_b32 v82, v89 offset:1024
	s_waitcnt lgkmcnt(3)
	v_lshl_add_u32 v145, v70, 10, v92
	global_load_dwordx4 v[18:21], v145, s[98:99]
	v_lshl_add_u32 v147, v71, 10, v92
	global_load_dwordx4 v[22:25], v147, s[98:99]
	v_lshl_add_u32 v145, v72, 10, v92
	global_load_dwordx4 v[26:29], v145, s[98:99]
	v_lshl_add_u32 v147, v73, 10, v92
	global_load_dwordx4 v[30:33], v147, s[98:99]
	ds_read_b32 v83, v89 offset:2560
	s_waitcnt lgkmcnt(3)
	v_lshl_add_u32 v145, v74, 10, v92
	global_load_dwordx4 v[34:37], v145, s[98:99]
	v_lshl_add_u32 v147, v75, 10, v92
	global_load_dwordx4 v[38:41], v147, s[98:99]
	v_lshl_add_u32 v145, v76, 10, v92
	global_load_dwordx4 v[42:45], v145, s[98:99]
	v_lshl_add_u32 v147, v77, 10, v92
	global_load_dwordx4 v[46:49], v147, s[98:99]
	ds_read_b32 v84, v89 offset:4096
	s_waitcnt lgkmcnt(3)
	v_lshl_add_u32 v145, v78, 10, v92
	global_load_dwordx4 v[50:53], v145, s[98:99]
	v_lshl_add_u32 v147, v79, 10, v92
	global_load_dwordx4 v[54:57], v147, s[98:99]
	v_lshl_add_u32 v145, v80, 10, v92
	global_load_dwordx4 v[58:61], v145, s[98:99]
	v_lshl_add_u32 v147, v81, 10, v92
	global_load_dwordx4 v[62:65], v147, s[98:99]
	ds_read_b32 v85, v89 offset:5632
	ds_read_b128 v[66:69], v91 offset:6144
	ds_read_b128 v[70:73], v91 offset:7680
	ds_read_b128 v[74:77], v91 offset:9216
	ds_read_b128 v[78:81], v91 offset:10752
	s_add_i32 s10, s34, 1
	s_min_u32 s10, s10, 31
	s_sub_i32 s11, s34, 1
	s_max_i32 s11, s11, 0
	s_cmp_lg_u64 s[0:1], 0
	s_cselect_b32 s35, s10, s11
	s_lshl_b32 s36, s35, 4
	v_add_u32_e32 v90, s36, v181
	s_add_i32 s10, s93, s36
	s_waitcnt vmcnt(12) lgkmcnt(0)
	v_mov_b32_e32 v91, s10
	v_mul_f32_e32 v88, v141, v82
	v_mfma_f32_16x16x32_fp8_fp8 v[184:187], v[2:3], v[122:123], 0
	v_mfma_f32_16x16x32_fp8_fp8 v[188:191], v[6:7], v[122:123], 0
	v_mfma_f32_16x16x32_fp8_fp8 v[192:195], v[10:11], v[122:123], 0
	v_mfma_f32_16x16x32_fp8_fp8 v[196:199], v[14:15], v[122:123], 0
	v_mfma_f32_16x16x32_fp8_fp8 v[184:187], v[4:5], v[124:125], v[184:187]
	v_mfma_f32_16x16x32_fp8_fp8 v[188:191], v[8:9], v[124:125], v[188:191]
	v_mfma_f32_16x16x32_fp8_fp8 v[192:195], v[12:13], v[124:125], v[192:195]
	v_mfma_f32_16x16x32_fp8_fp8 v[196:199], v[16:17], v[124:125], v[196:199]
	v_lshl_add_u32 v145, v66, 10, v92
	global_load_dwordx4 v[2:5], v145, s[98:99]
	v_lshl_add_u32 v147, v67, 10, v92
	global_load_dwordx4 v[6:9], v147, s[98:99]
	v_lshl_add_u32 v145, v68, 10, v92
	global_load_dwordx4 v[10:13], v145, s[98:99]
	v_lshl_add_u32 v147, v69, 10, v92
	global_load_dwordx4 v[14:17], v147, s[98:99]
	ds_read_b32 v82, v89 offset:7168
	ds_read_b128 v[66:69], v91 offset:0
.Lus_loop:
	s_barrier
	s_waitcnt vmcnt(12) lgkmcnt(10)
	v_mul_f32_e32 v1, v140, v83
	v_cndmask_b32_e64 v184, v185, v184, s[2:3]
	v_cndmask_b32_e64 v185, v187, v186, s[2:3]
	v_mfma_f32_16x16x32_fp8_fp8 v[200:203], v[18:19], v[118:119], 0
	v_cndmask_b32_e64 v188, v189, v188, s[2:3]
	v_cndmask_b32_e64 v189, v191, v190, s[2:3]
	v_mfma_f32_16x16x32_fp8_fp8 v[204:207], v[22:23], v[118:119], 0
	v_cndmask_b32_e64 v192, v193, v192, s[2:3]
	v_cndmask_b32_e64 v193, v195, v194, s[2:3]
	v_mfma_f32_16x16x32_fp8_fp8 v[228:231], v[26:27], v[118:119], 0
	v_cndmask_b32_e64 v196, v197, v196, s[2:3]
	v_cndmask_b32_e64 v197, v199, v198, s[2:3]
	v_mfma_f32_16x16x32_fp8_fp8 v[232:235], v[30:31], v[118:119], 0
	v_cndmask_b32_e64 v184, v185, v184, s[4:5]
	v_cndmask_b32_e64 v188, v189, v188, s[4:5]
	v_cndmask_b32_e64 v192, v193, v192, s[4:5]
	v_cndmask_b32_e64 v196, v197, v196, s[4:5]
	v_mfma_f32_16x16x32_fp8_fp8 v[200:203], v[20:21], v[120:121], v[200:203]
	v_cndmask_b32_e64 v146, v188, v184, s[2:3]
	v_cndmask_b32_e64 v143, v184, v188, s[2:3]
	v_cndmask_b32_e64 v142, v196, v192, s[2:3]
	v_cndmask_b32_e64 v144, v192, v196, s[2:3]
	v_mfma_f32_16x16x32_fp8_fp8 v[204:207], v[24:25], v[120:121], v[204:207]
	v_add_f32_dpp v146, v143, v146 quad_perm:[1,0,3,2] row_mask:0xf bank_mask:0xf bound_ctrl:1
	v_add_f32_dpp v142, v144, v142 quad_perm:[1,0,3,2] row_mask:0xf bank_mask:0xf bound_ctrl:1
	v_mfma_f32_16x16x32_fp8_fp8 v[228:231], v[28:29], v[120:121], v[228:231]
	v_cndmask_b32_e64 v143, v142, v146, s[4:5]
	v_cndmask_b32_e64 v86, v146, v142, s[4:5]
	v_mfma_f32_16x16x32_fp8_fp8 v[232:235], v[32:33], v[120:121], v[232:235]
	v_lshl_add_u32 v145, v70, 10, v92
	global_load_dwordx4 v[18:21], v145, s[98:99]
	v_add_f32_dpp v86, v86, v143 quad_perm:[2,3,0,1] row_mask:0xf bank_mask:0xf bound_ctrl:1
	v_cndmask_b32_e64 v86, 0, v86, s[6:7]
	v_lshl_add_u32 v147, v71, 10, v92
	global_load_dwordx4 v[22:25], v147, s[98:99]
	v_add_f32_dpp v86, v86, v86 row_ror:4 row_mask:0xf bank_mask:0xf bound_ctrl:1
	v_lshl_add_u32 v145, v72, 10, v92
	global_load_dwordx4 v[26:29], v145, s[98:99]
	v_add_f32_dpp v86, v86, v86 row_ror:8 row_mask:0xf bank_mask:0xf bound_ctrl:1
	v_mov_b32_e32 v87, v86
	v_lshl_add_u32 v147, v73, 10, v92
	global_load_dwordx4 v[30:33], v147, s[98:99]
	v_permlane16_swap_b32_e32 v86, v87
	v_add_f32_e32 v86, v86, v87
	v_mov_b32_e32 v87, v86
	ds_read_b32 v83, v89 offset:8704
	ds_read_b128 v[70:73], v91 offset:1536
	v_permlane32_swap_b32 v86, v87
	v_add_f32_e32 v86, v86, v87
	v_mul_f32_e32 v93, v88, v86
	s_mov_b64 exec, s[8:9]
	ds_write_b32 v89, v93 offset:1024
	s_mov_b64 exec, -1
	s_waitcnt vmcnt(12) lgkmcnt(10)
	v_mul_f32_e32 v88, v139, v84
	v_cndmask_b32_e64 v200, v201, v200, s[2:3]
	v_cndmask_b32_e64 v201, v203, v202, s[2:3]
	v_mfma_f32_16x16x32_fp8_fp8 v[184:187], v[34:35], v[114:115], 0
	v_cndmask_b32_e64 v204, v205, v204, s[2:3]
	v_cndmask_b32_e64 v205, v207, v206, s[2:3]
	v_mfma_f32_16x16x32_fp8_fp8 v[188:191], v[38:39], v[114:115], 0
	v_cndmask_b32_e64 v228, v229, v228, s[2:3]
	v_cndmask_b32_e64 v229, v231, v230, s[2:3]
	v_mfma_f32_16x16x32_fp8_fp8 v[192:195], v[42:43], v[114:115], 0
	v_cndmask_b32_e64 v232, v233, v232, s[2:3]
	v_cndmask_b32_e64 v233, v235, v234, s[2:3]
	v_mfma_f32_16x16x32_fp8_fp8 v[196:199], v[46:47], v[114:115], 0
	v_cndmask_b32_e64 v200, v201, v200, s[4:5]
	v_cndmask_b32_e64 v204, v205, v204, s[4:5]
	v_cndmask_b32_e64 v228, v229, v228, s[4:5]
	v_cndmask_b32_e64 v232, v233, v232, s[4:5]
	v_mfma_f32_16x16x32_fp8_fp8 v[184:187], v[36:37], v[116:117], v[184:187]
	v_cndmask_b32_e64 v146, v204, v200, s[2:3]
	v_cndmask_b32_e64 v143, v200, v204, s[2:3]
	v_cndmask_b32_e64 v142, v232, v228, s[2:3]
	v_cndmask_b32_e64 v144, v228, v232, s[2:3]
	v_mfma_f32_16x16x32_fp8_fp8 v[188:191], v[40:41], v[116:117], v[188:191]
	v_add_f32_dpp v146, v143, v146 quad_perm:[1,0,3,2] row_mask:0xf bank_mask:0xf bound_ctrl:1
	v_add_f32_dpp v142, v144, v142 quad_perm:[1,0,3,2] row_mask:0xf bank_mask:0xf bound_ctrl:1
	v_mfma_f32_16x16x32_fp8_fp8 v[192:195], v[44:45], v[116:117], v[192:195]
	v_cndmask_b32_e64 v143, v142, v146, s[4:5]
	v_cndmask_b32_e64 v86, v146, v142, s[4:5]
	v_mfma_f32_16x16x32_fp8_fp8 v[196:199], v[48:49], v[116:117], v[196:199]
	v_lshl_add_u32 v145, v74, 10, v92
	global_load_dwordx4 v[34:37], v145, s[98:99]
	v_add_f32_dpp v86, v86, v143 quad_perm:[2,3,0,1] row_mask:0xf bank_mask:0xf bound_ctrl:1
	v_cndmask_b32_e64 v86, 0, v86, s[6:7]
	v_lshl_add_u32 v147, v75, 10, v92
	global_load_dwordx4 v[38:41], v147, s[98:99]
	v_add_f32_dpp v86, v86, v86 row_ror:4 row_mask:0xf bank_mask:0xf bound_ctrl:1
	v_lshl_add_u32 v145, v76, 10, v92
	global_load_dwordx4 v[42:45], v145, s[98:99]
	v_add_f32_dpp v86, v86, v86 row_ror:8 row_mask:0xf bank_mask:0xf bound_ctrl:1
	v_mov_b32_e32 v87, v86
	v_lshl_add_u32 v147, v77, 10, v92
	global_load_dwordx4 v[46:49], v147, s[98:99]
	v_permlane16_swap_b32_e32 v86, v87
	v_add_f32_e32 v86, v86, v87
	v_mov_b32_e32 v87, v86
	ds_read_b32 v84, v89 offset:10240
	ds_read_b128 v[74:77], v91 offset:3072
	v_permlane32_swap_b32 v86, v87
	v_add_f32_e32 v86, v86, v87
	v_mul_f32_e32 v93, v1, v86
	s_mov_b64 exec, s[8:9]
	ds_write_b32 v89, v93 offset:2560
	s_mov_b64 exec, -1
	s_waitcnt vmcnt(12) lgkmcnt(10)
	v_mul_f32_e32 v1, v138, v85
	v_cndmask_b32_e64 v184, v185, v184, s[2:3]
	v_cndmask_b32_e64 v185, v187, v186, s[2:3]
	v_mfma_f32_16x16x32_fp8_fp8 v[200:203], v[50:51], v[110:111], 0
	v_cndmask_b32_e64 v188, v189, v188, s[2:3]
	v_cndmask_b32_e64 v189, v191, v190, s[2:3]
	v_mfma_f32_16x16x32_fp8_fp8 v[204:207], v[54:55], v[110:111], 0
	v_cndmask_b32_e64 v192, v193, v192, s[2:3]
	v_cndmask_b32_e64 v193, v195, v194, s[2:3]
	v_mfma_f32_16x16x32_fp8_fp8 v[228:231], v[58:59], v[110:111], 0
	v_cndmask_b32_e64 v196, v197, v196, s[2:3]
	v_cndmask_b32_e64 v197, v199, v198, s[2:3]
	v_mfma_f32_16x16x32_fp8_fp8 v[232:235], v[62:63], v[110:111], 0
	v_cndmask_b32_e64 v184, v185, v184, s[4:5]
	v_cndmask_b32_e64 v188, v189, v188, s[4:5]
	v_cndmask_b32_e64 v192, v193, v192, s[4:5]
	v_cndmask_b32_e64 v196, v197, v196, s[4:5]
	v_mfma_f32_16x16x32_fp8_fp8 v[200:203], v[52:53], v[112:113], v[200:203]
	v_cndmask_b32_e64 v146, v188, v184, s[2:3]
	v_cndmask_b32_e64 v143, v184, v188, s[2:3]
	v_cndmask_b32_e64 v142, v196, v192, s[2:3]
	v_cndmask_b32_e64 v144, v192, v196, s[2:3]
	v_mfma_f32_16x16x32_fp8_fp8 v[204:207], v[56:57], v[112:113], v[204:207]
	v_add_f32_dpp v146, v143, v146 quad_perm:[1,0,3,2] row_mask:0xf bank_mask:0xf bound_ctrl:1
	v_add_f32_dpp v142, v144, v142 quad_perm:[1,0,3,2] row_mask:0xf bank_mask:0xf bound_ctrl:1
	v_mfma_f32_16x16x32_fp8_fp8 v[228:231], v[60:61], v[112:113], v[228:231]
	v_cndmask_b32_e64 v143, v142, v146, s[4:5]
	v_cndmask_b32_e64 v86, v146, v142, s[4:5]
	v_mfma_f32_16x16x32_fp8_fp8 v[232:235], v[64:65], v[112:113], v[232:235]
	v_lshl_add_u32 v145, v78, 10, v92
	global_load_dwordx4 v[50:53], v145, s[98:99]
	v_add_f32_dpp v86, v86, v143 quad_perm:[2,3,0,1] row_mask:0xf bank_mask:0xf bound_ctrl:1
	v_cndmask_b32_e64 v86, 0, v86, s[6:7]
	v_lshl_add_u32 v147, v79, 10, v92
	global_load_dwordx4 v[54:57], v147, s[98:99]
	v_add_f32_dpp v86, v86, v86 row_ror:4 row_mask:0xf bank_mask:0xf bound_ctrl:1
	v_lshl_add_u32 v145, v80, 10, v92
	global_load_dwordx4 v[58:61], v145, s[98:99]
	v_add_f32_dpp v86, v86, v86 row_ror:8 row_mask:0xf bank_mask:0xf bound_ctrl:1
	v_mov_b32_e32 v87, v86
	v_lshl_add_u32 v147, v81, 10, v92
	global_load_dwordx4 v[62:65], v147, s[98:99]
	v_permlane16_swap_b32_e32 v86, v87
	v_add_f32_e32 v86, v86, v87
	v_mov_b32_e32 v87, v86
	ds_read_b32 v85, v89 offset:11776
	ds_read_b128 v[78:81], v91 offset:4608
	v_permlane32_swap_b32 v86, v87
	v_add_f32_e32 v86, v86, v87
	v_mul_f32_e32 v93, v88, v86
	s_mov_b64 exec, s[8:9]
	ds_write_b32 v89, v93 offset:4096
	s_mov_b64 exec, -1
	s_waitcnt vmcnt(12) lgkmcnt(10)
	v_mul_f32_e32 v88, v137, v82
	v_cndmask_b32_e64 v200, v201, v200, s[2:3]
	v_cndmask_b32_e64 v201, v203, v202, s[2:3]
	v_mfma_f32_16x16x32_fp8_fp8 v[184:187], v[2:3], v[106:107], 0
	v_cndmask_b32_e64 v204, v205, v204, s[2:3]
	v_cndmask_b32_e64 v205, v207, v206, s[2:3]
	v_mfma_f32_16x16x32_fp8_fp8 v[188:191], v[6:7], v[106:107], 0
	v_cndmask_b32_e64 v228, v229, v228, s[2:3]
	v_cndmask_b32_e64 v229, v231, v230, s[2:3]
	v_mfma_f32_16x16x32_fp8_fp8 v[192:195], v[10:11], v[106:107], 0
	v_cndmask_b32_e64 v232, v233, v232, s[2:3]
	v_cndmask_b32_e64 v233, v235, v234, s[2:3]
	v_mfma_f32_16x16x32_fp8_fp8 v[196:199], v[14:15], v[106:107], 0
	v_cndmask_b32_e64 v200, v201, v200, s[4:5]
	v_cndmask_b32_e64 v204, v205, v204, s[4:5]
	v_cndmask_b32_e64 v228, v229, v228, s[4:5]
	v_cndmask_b32_e64 v232, v233, v232, s[4:5]
	v_mfma_f32_16x16x32_fp8_fp8 v[184:187], v[4:5], v[108:109], v[184:187]
	v_cndmask_b32_e64 v146, v204, v200, s[2:3]
	v_cndmask_b32_e64 v143, v200, v204, s[2:3]
	v_cndmask_b32_e64 v142, v232, v228, s[2:3]
	v_cndmask_b32_e64 v144, v228, v232, s[2:3]
	v_mfma_f32_16x16x32_fp8_fp8 v[188:191], v[8:9], v[108:109], v[188:191]
	v_add_f32_dpp v146, v143, v146 quad_perm:[1,0,3,2] row_mask:0xf bank_mask:0xf bound_ctrl:1
	v_add_f32_dpp v142, v144, v142 quad_perm:[1,0,3,2] row_mask:0xf bank_mask:0xf bound_ctrl:1
	v_mfma_f32_16x16x32_fp8_fp8 v[192:195], v[12:13], v[108:109], v[192:195]
	v_cndmask_b32_e64 v143, v142, v146, s[4:5]
	v_cndmask_b32_e64 v86, v146, v142, s[4:5]
	v_mfma_f32_16x16x32_fp8_fp8 v[196:199], v[16:17], v[108:109], v[196:199]
	v_lshl_add_u32 v145, v66, 10, v92
	global_load_dwordx4 v[2:5], v145, s[98:99]
	v_add_f32_dpp v86, v86, v143 quad_perm:[2,3,0,1] row_mask:0xf bank_mask:0xf bound_ctrl:1
	v_cndmask_b32_e64 v86, 0, v86, s[6:7]
	v_lshl_add_u32 v147, v67, 10, v92
	global_load_dwordx4 v[6:9], v147, s[98:99]
	v_add_f32_dpp v86, v86, v86 row_ror:4 row_mask:0xf bank_mask:0xf bound_ctrl:1
	v_lshl_add_u32 v145, v68, 10, v92
	global_load_dwordx4 v[10:13], v145, s[98:99]
	v_add_f32_dpp v86, v86, v86 row_ror:8 row_mask:0xf bank_mask:0xf bound_ctrl:1
	v_mov_b32_e32 v87, v86
	v_lshl_add_u32 v147, v69, 10, v92
	global_load_dwordx4 v[14:17], v147, s[98:99]
	v_permlane16_swap_b32_e32 v86, v87
	v_add_f32_e32 v86, v86, v87
	v_mov_b32_e32 v87, v86
	ds_read_b32 v82, v90 offset:1024
	ds_read_b128 v[66:69], v91 offset:6144
	v_permlane32_swap_b32 v86, v87
	v_add_f32_e32 v86, v86, v87
	v_mul_f32_e32 v93, v1, v86
	s_mov_b64 exec, s[8:9]
	ds_write_b32 v89, v93 offset:5632
	s_mov_b64 exec, -1
	s_waitcnt vmcnt(12) lgkmcnt(10)
	v_mul_f32_e32 v1, v136, v83
	v_cndmask_b32_e64 v184, v185, v184, s[2:3]
	v_cndmask_b32_e64 v185, v187, v186, s[2:3]
	v_mfma_f32_16x16x32_fp8_fp8 v[200:203], v[18:19], v[102:103], 0
	v_cndmask_b32_e64 v188, v189, v188, s[2:3]
	v_cndmask_b32_e64 v189, v191, v190, s[2:3]
	v_mfma_f32_16x16x32_fp8_fp8 v[204:207], v[22:23], v[102:103], 0
	v_cndmask_b32_e64 v192, v193, v192, s[2:3]
	v_cndmask_b32_e64 v193, v195, v194, s[2:3]
	v_mfma_f32_16x16x32_fp8_fp8 v[228:231], v[26:27], v[102:103], 0
	v_cndmask_b32_e64 v196, v197, v196, s[2:3]
	v_cndmask_b32_e64 v197, v199, v198, s[2:3]
	v_mfma_f32_16x16x32_fp8_fp8 v[232:235], v[30:31], v[102:103], 0
	v_cndmask_b32_e64 v184, v185, v184, s[4:5]
	v_cndmask_b32_e64 v188, v189, v188, s[4:5]
	v_cndmask_b32_e64 v192, v193, v192, s[4:5]
	v_cndmask_b32_e64 v196, v197, v196, s[4:5]
	v_mfma_f32_16x16x32_fp8_fp8 v[200:203], v[20:21], v[104:105], v[200:203]
	v_cndmask_b32_e64 v146, v188, v184, s[2:3]
	v_cndmask_b32_e64 v143, v184, v188, s[2:3]
	v_cndmask_b32_e64 v142, v196, v192, s[2:3]
	v_cndmask_b32_e64 v144, v192, v196, s[2:3]
	v_mfma_f32_16x16x32_fp8_fp8 v[204:207], v[24:25], v[104:105], v[204:207]
	v_add_f32_dpp v146, v143, v146 quad_perm:[1,0,3,2] row_mask:0xf bank_mask:0xf bound_ctrl:1
	v_add_f32_dpp v142, v144, v142 quad_perm:[1,0,3,2] row_mask:0xf bank_mask:0xf bound_ctrl:1
	v_mfma_f32_16x16x32_fp8_fp8 v[228:231], v[28:29], v[104:105], v[228:231]
	v_cndmask_b32_e64 v143, v142, v146, s[4:5]
	v_cndmask_b32_e64 v86, v146, v142, s[4:5]
	v_mfma_f32_16x16x32_fp8_fp8 v[232:235], v[32:33], v[104:105], v[232:235]
	v_lshl_add_u32 v145, v70, 10, v92
	global_load_dwordx4 v[18:21], v145, s[98:99]
	v_add_f32_dpp v86, v86, v143 quad_perm:[2,3,0,1] row_mask:0xf bank_mask:0xf bound_ctrl:1
	v_cndmask_b32_e64 v86, 0, v86, s[6:7]
	v_lshl_add_u32 v147, v71, 10, v92
	global_load_dwordx4 v[22:25], v147, s[98:99]
	v_add_f32_dpp v86, v86, v86 row_ror:4 row_mask:0xf bank_mask:0xf bound_ctrl:1
	v_lshl_add_u32 v145, v72, 10, v92
	global_load_dwordx4 v[26:29], v145, s[98:99]
	v_add_f32_dpp v86, v86, v86 row_ror:8 row_mask:0xf bank_mask:0xf bound_ctrl:1
	v_mov_b32_e32 v87, v86
	v_lshl_add_u32 v147, v73, 10, v92
	global_load_dwordx4 v[30:33], v147, s[98:99]
	v_permlane16_swap_b32_e32 v86, v87
	v_add_f32_e32 v86, v86, v87
	v_mov_b32_e32 v87, v86
	ds_read_b32 v83, v90 offset:2560
	ds_read_b128 v[70:73], v91 offset:7680
	v_permlane32_swap_b32 v86, v87
	v_add_f32_e32 v86, v86, v87
	v_mul_f32_e32 v93, v88, v86
	s_mov_b64 exec, s[8:9]
	ds_write_b32 v89, v93 offset:7168
	s_mov_b64 exec, -1
	s_waitcnt vmcnt(12) lgkmcnt(10)
	v_mul_f32_e32 v88, v129, v84
	v_cndmask_b32_e64 v200, v201, v200, s[2:3]
	v_cndmask_b32_e64 v201, v203, v202, s[2:3]
	v_mfma_f32_16x16x32_fp8_fp8 v[184:187], v[34:35], v[98:99], 0
	v_cndmask_b32_e64 v204, v205, v204, s[2:3]
	v_cndmask_b32_e64 v205, v207, v206, s[2:3]
	v_mfma_f32_16x16x32_fp8_fp8 v[188:191], v[38:39], v[98:99], 0
	v_cndmask_b32_e64 v228, v229, v228, s[2:3]
	v_cndmask_b32_e64 v229, v231, v230, s[2:3]
	v_mfma_f32_16x16x32_fp8_fp8 v[192:195], v[42:43], v[98:99], 0
	v_cndmask_b32_e64 v232, v233, v232, s[2:3]
	v_cndmask_b32_e64 v233, v235, v234, s[2:3]
	v_mfma_f32_16x16x32_fp8_fp8 v[196:199], v[46:47], v[98:99], 0
	v_cndmask_b32_e64 v200, v201, v200, s[4:5]
	v_cndmask_b32_e64 v204, v205, v204, s[4:5]
	v_cndmask_b32_e64 v228, v229, v228, s[4:5]
	v_cndmask_b32_e64 v232, v233, v232, s[4:5]
	v_mfma_f32_16x16x32_fp8_fp8 v[184:187], v[36:37], v[100:101], v[184:187]
	v_cndmask_b32_e64 v146, v204, v200, s[2:3]
	v_cndmask_b32_e64 v143, v200, v204, s[2:3]
	v_cndmask_b32_e64 v142, v232, v228, s[2:3]
	v_cndmask_b32_e64 v144, v228, v232, s[2:3]
	v_mfma_f32_16x16x32_fp8_fp8 v[188:191], v[40:41], v[100:101], v[188:191]
	v_add_f32_dpp v146, v143, v146 quad_perm:[1,0,3,2] row_mask:0xf bank_mask:0xf bound_ctrl:1
	v_add_f32_dpp v142, v144, v142 quad_perm:[1,0,3,2] row_mask:0xf bank_mask:0xf bound_ctrl:1
	v_mfma_f32_16x16x32_fp8_fp8 v[192:195], v[44:45], v[100:101], v[192:195]
	v_cndmask_b32_e64 v143, v142, v146, s[4:5]
	v_cndmask_b32_e64 v86, v146, v142, s[4:5]
	v_mfma_f32_16x16x32_fp8_fp8 v[196:199], v[48:49], v[100:101], v[196:199]
	v_lshl_add_u32 v145, v74, 10, v92
	global_load_dwordx4 v[34:37], v145, s[98:99]
	v_add_f32_dpp v86, v86, v143 quad_perm:[2,3,0,1] row_mask:0xf bank_mask:0xf bound_ctrl:1
	v_cndmask_b32_e64 v86, 0, v86, s[6:7]
	v_lshl_add_u32 v147, v75, 10, v92
	global_load_dwordx4 v[38:41], v147, s[98:99]
	v_add_f32_dpp v86, v86, v86 row_ror:4 row_mask:0xf bank_mask:0xf bound_ctrl:1
	v_lshl_add_u32 v145, v76, 10, v92
	global_load_dwordx4 v[42:45], v145, s[98:99]
	v_add_f32_dpp v86, v86, v86 row_ror:8 row_mask:0xf bank_mask:0xf bound_ctrl:1
	v_mov_b32_e32 v87, v86
	v_lshl_add_u32 v147, v77, 10, v92
	global_load_dwordx4 v[46:49], v147, s[98:99]
	v_permlane16_swap_b32_e32 v86, v87
	v_add_f32_e32 v86, v86, v87
	v_mov_b32_e32 v87, v86
	ds_read_b32 v84, v90 offset:4096
	ds_read_b128 v[74:77], v91 offset:9216
	v_permlane32_swap_b32 v86, v87
	v_add_f32_e32 v86, v86, v87
	v_mul_f32_e32 v93, v1, v86
	s_mov_b64 exec, s[8:9]
	ds_write_b32 v89, v93 offset:8704
	s_mov_b64 exec, -1
	s_waitcnt vmcnt(12) lgkmcnt(10)
	v_mul_f32_e32 v1, v128, v85
	v_cndmask_b32_e64 v184, v185, v184, s[2:3]
	v_cndmask_b32_e64 v185, v187, v186, s[2:3]
	v_mfma_f32_16x16x32_fp8_fp8 v[200:203], v[50:51], v[94:95], 0
	v_cndmask_b32_e64 v188, v189, v188, s[2:3]
	v_cndmask_b32_e64 v189, v191, v190, s[2:3]
	v_mfma_f32_16x16x32_fp8_fp8 v[204:207], v[54:55], v[94:95], 0
	v_cndmask_b32_e64 v192, v193, v192, s[2:3]
	v_cndmask_b32_e64 v193, v195, v194, s[2:3]
	v_mfma_f32_16x16x32_fp8_fp8 v[228:231], v[58:59], v[94:95], 0
	v_cndmask_b32_e64 v196, v197, v196, s[2:3]
	v_cndmask_b32_e64 v197, v199, v198, s[2:3]
	v_mfma_f32_16x16x32_fp8_fp8 v[232:235], v[62:63], v[94:95], 0
	v_cndmask_b32_e64 v184, v185, v184, s[4:5]
	v_cndmask_b32_e64 v188, v189, v188, s[4:5]
	v_cndmask_b32_e64 v192, v193, v192, s[4:5]
	v_cndmask_b32_e64 v196, v197, v196, s[4:5]
	v_mfma_f32_16x16x32_fp8_fp8 v[200:203], v[52:53], v[96:97], v[200:203]
	v_cndmask_b32_e64 v146, v188, v184, s[2:3]
	v_cndmask_b32_e64 v143, v184, v188, s[2:3]
	v_cndmask_b32_e64 v142, v196, v192, s[2:3]
	v_cndmask_b32_e64 v144, v192, v196, s[2:3]
	v_mfma_f32_16x16x32_fp8_fp8 v[204:207], v[56:57], v[96:97], v[204:207]
	v_add_f32_dpp v146, v143, v146 quad_perm:[1,0,3,2] row_mask:0xf bank_mask:0xf bound_ctrl:1
	v_add_f32_dpp v142, v144, v142 quad_perm:[1,0,3,2] row_mask:0xf bank_mask:0xf bound_ctrl:1
	v_mfma_f32_16x16x32_fp8_fp8 v[228:231], v[60:61], v[96:97], v[228:231]
	v_cndmask_b32_e64 v143, v142, v146, s[4:5]
	v_cndmask_b32_e64 v86, v146, v142, s[4:5]
	v_mfma_f32_16x16x32_fp8_fp8 v[232:235], v[64:65], v[96:97], v[232:235]
	v_lshl_add_u32 v145, v78, 10, v92
	global_load_dwordx4 v[50:53], v145, s[98:99]
	v_add_f32_dpp v86, v86, v143 quad_perm:[2,3,0,1] row_mask:0xf bank_mask:0xf bound_ctrl:1
	v_cndmask_b32_e64 v86, 0, v86, s[6:7]
	v_lshl_add_u32 v147, v79, 10, v92
	global_load_dwordx4 v[54:57], v147, s[98:99]
	v_add_f32_dpp v86, v86, v86 row_ror:4 row_mask:0xf bank_mask:0xf bound_ctrl:1
	v_lshl_add_u32 v145, v80, 10, v92
	global_load_dwordx4 v[58:61], v145, s[98:99]
	v_add_f32_dpp v86, v86, v86 row_ror:8 row_mask:0xf bank_mask:0xf bound_ctrl:1
	v_mov_b32_e32 v87, v86
	v_lshl_add_u32 v147, v81, 10, v92
	global_load_dwordx4 v[62:65], v147, s[98:99]
	v_permlane16_swap_b32_e32 v86, v87
	v_add_f32_e32 v86, v86, v87
	v_mov_b32_e32 v87, v86
	ds_read_b32 v85, v90 offset:5632
	ds_read_b128 v[78:81], v91 offset:10752
	v_permlane32_swap_b32 v86, v87
	v_add_f32_e32 v86, v86, v87
	v_mul_f32_e32 v93, v88, v86
	s_mov_b64 exec, s[8:9]
	ds_write_b32 v89, v93 offset:10240
	s_mov_b64 exec, -1
	s_waitcnt vmcnt(12) lgkmcnt(10)
	s_add_i32 s10, s35, 1
	s_min_u32 s10, s10, 31
	s_sub_i32 s11, s35, 1
	s_max_i32 s11, s11, 0
	s_cmp_lg_u64 s[0:1], 0
	s_cselect_b32 s72, s10, s11
	s_lshl_b32 s36, s72, 4
	s_add_i32 s10, s93, s36
	v_mov_b32_e32 v91, s10
	v_mul_f32_e32 v88, v141, v82
	v_cndmask_b32_e64 v200, v201, v200, s[2:3]
	v_cndmask_b32_e64 v201, v203, v202, s[2:3]
	v_mfma_f32_16x16x32_fp8_fp8 v[184:187], v[2:3], v[122:123], 0
	v_cndmask_b32_e64 v204, v205, v204, s[2:3]
	v_cndmask_b32_e64 v205, v207, v206, s[2:3]
	v_mfma_f32_16x16x32_fp8_fp8 v[188:191], v[6:7], v[122:123], 0
	v_cndmask_b32_e64 v228, v229, v228, s[2:3]
	v_cndmask_b32_e64 v229, v231, v230, s[2:3]
	v_mfma_f32_16x16x32_fp8_fp8 v[192:195], v[10:11], v[122:123], 0
	v_cndmask_b32_e64 v232, v233, v232, s[2:3]
	v_cndmask_b32_e64 v233, v235, v234, s[2:3]
	v_mfma_f32_16x16x32_fp8_fp8 v[196:199], v[14:15], v[122:123], 0
	v_cndmask_b32_e64 v200, v201, v200, s[4:5]
	v_cndmask_b32_e64 v204, v205, v204, s[4:5]
	v_cndmask_b32_e64 v228, v229, v228, s[4:5]
	v_cndmask_b32_e64 v232, v233, v232, s[4:5]
	v_mfma_f32_16x16x32_fp8_fp8 v[184:187], v[4:5], v[124:125], v[184:187]
	v_cndmask_b32_e64 v146, v204, v200, s[2:3]
	v_cndmask_b32_e64 v143, v200, v204, s[2:3]
	v_cndmask_b32_e64 v142, v232, v228, s[2:3]
	v_cndmask_b32_e64 v144, v228, v232, s[2:3]
	v_mfma_f32_16x16x32_fp8_fp8 v[188:191], v[8:9], v[124:125], v[188:191]
	v_add_f32_dpp v146, v143, v146 quad_perm:[1,0,3,2] row_mask:0xf bank_mask:0xf bound_ctrl:1
	v_add_f32_dpp v142, v144, v142 quad_perm:[1,0,3,2] row_mask:0xf bank_mask:0xf bound_ctrl:1
	v_mfma_f32_16x16x32_fp8_fp8 v[192:195], v[12:13], v[124:125], v[192:195]
	v_cndmask_b32_e64 v143, v142, v146, s[4:5]
	v_cndmask_b32_e64 v86, v146, v142, s[4:5]
	v_mfma_f32_16x16x32_fp8_fp8 v[196:199], v[16:17], v[124:125], v[196:199]
	v_lshl_add_u32 v145, v66, 10, v92
	global_load_dwordx4 v[2:5], v145, s[98:99]
	v_add_f32_dpp v86, v86, v143 quad_perm:[2,3,0,1] row_mask:0xf bank_mask:0xf bound_ctrl:1
	v_cndmask_b32_e64 v86, 0, v86, s[6:7]
	v_lshl_add_u32 v147, v67, 10, v92
	global_load_dwordx4 v[6:9], v147, s[98:99]
	v_add_f32_dpp v86, v86, v86 row_ror:4 row_mask:0xf bank_mask:0xf bound_ctrl:1
	v_lshl_add_u32 v145, v68, 10, v92
	global_load_dwordx4 v[10:13], v145, s[98:99]
	v_add_f32_dpp v86, v86, v86 row_ror:8 row_mask:0xf bank_mask:0xf bound_ctrl:1
	v_mov_b32_e32 v87, v86
	v_lshl_add_u32 v147, v69, 10, v92
	global_load_dwordx4 v[14:17], v147, s[98:99]
	v_permlane16_swap_b32_e32 v86, v87
	v_add_f32_e32 v86, v86, v87
	v_mov_b32_e32 v87, v86
	ds_read_b32 v82, v90 offset:7168
	ds_read_b128 v[66:69], v91 offset:0
	v_permlane32_swap_b32 v86, v87
	v_add_f32_e32 v86, v86, v87
	v_mul_f32_e32 v93, v1, v86
	s_mov_b64 exec, s[8:9]
	ds_write_b32 v89, v93 offset:11776
	s_mov_b64 exec, -1
	v_mov_b32_e32 v89, v90
	v_add_u32_e32 v90, s36, v181
	s_mov_b32 s34, s35
	s_mov_b32 s35, s72
	s_add_i32 s95, s95, 1
	s_cmp_eq_u32 s95, 32
	s_cbranch_scc0 .Lus_loop
	s_waitcnt vmcnt(0) lgkmcnt(0)
	s_waitcnt lgkmcnt(0)
	s_waitcnt vmcnt(4)
	ds_read2st64_b32 v[2:3], v178 offset0:2 offset1:3
	ds_read2st64_b32 v[4:5], v178 offset0:4 offset1:5
	s_mov_b32 s0, 0x3e6d3388
	s_waitcnt lgkmcnt(0)
	v_fma_f32 v1, |v4|, s0, 1.0
	v_rcp_f32_e32 v1, v1
	v_cmp_gt_f32_e32 vcc, 0, v4
	v_fmamk_f32 v6, v1, 0x3f07dc22, v210
	v_fmaak_f32 v6, v1, v6, 0x3f35f0e3
	v_fmaak_f32 v6, v1, v6, 0xbe11a98e
	v_fmaak_f32 v6, v1, v6, 0x3e027906
	v_mul_f32_e32 v1, v1, v6
	v_mul_f32_e32 v6, v4, v4
	v_mul_f32_e32 v6, 0xbf38aa3b, v6
	v_exp_f32_e32 v6, v6
	s_nop 0
	v_mul_f32_e32 v1, v6, v1
	v_mul_f32_e32 v6, v4, v1
	v_fma_f32 v1, -v4, v1, v4
	v_cndmask_b32_e32 v1, v1, v6, vcc
	v_mul_f32_e32 v1, v2, v1
	v_fma_f32 v2, |v5|, s0, 1.0
	v_rcp_f32_e32 v2, v2
	v_cmp_gt_f32_e32 vcc, 0, v5
	v_fmamk_f32 v4, v2, 0x3f07dc22, v210
	v_fmaak_f32 v4, v2, v4, 0x3f35f0e3
	v_fmaak_f32 v4, v2, v4, 0xbe11a98e
	v_fmaak_f32 v4, v2, v4, 0x3e027906
	v_mul_f32_e32 v2, v2, v4
	v_mul_f32_e32 v4, v5, v5
	v_mul_f32_e32 v4, 0xbf38aa3b, v4
	v_exp_f32_e32 v4, v4
	s_nop 0
	v_mul_f32_e32 v2, v4, v2
	v_mul_f32_e32 v4, v5, v2
	v_fma_f32 v2, -v5, v2, v5
	v_cndmask_b32_e32 v2, v2, v4, vcc
	v_mul_f32_e32 v2, v3, v2
	v_max_f32_e64 v3, |v1|, |v2|
	s_nop 1
	v_mov_b32_dpp v4, v3 quad_perm:[1,0,3,2] row_mask:0xf bank_mask:0xf bound_ctrl:1
	v_max_f32_e32 v4, v4, v4
	v_max_f32_e32 v3, v3, v4
	s_nop 1
	v_mov_b32_dpp v4, v3 quad_perm:[2,3,0,1] row_mask:0xf bank_mask:0xf bound_ctrl:1
	v_max_f32_e32 v4, v4, v4
	v_max_f32_e32 v3, v3, v4
	s_nop 1
	v_mov_b32_dpp v4, v3 row_half_mirror row_mask:0xf bank_mask:0xf bound_ctrl:1
	v_max_f32_e32 v4, v4, v4
	v_max_f32_e32 v3, v3, v4
	s_nop 1
	v_mov_b32_dpp v4, v3 row_mirror row_mask:0xf bank_mask:0xf bound_ctrl:1
	v_max_f32_e32 v4, v4, v4
	v_max_f32_e32 v3, v3, v4
	s_nop 0
	v_readlane_b32 s0, v3, 0
	v_readlane_b32 s1, v3, 16
	v_readlane_b32 s10, v3, 32
	v_readlane_b32 s11, v3, 48
	v_max_f32_e64 v3, s1, s1
	v_max_f32_e64 v4, s0, s0
	v_max_f32_e32 v3, v4, v3
	v_max_f32_e64 v4, s11, s11
	v_max_f32_e64 v5, s10, s10
	v_max_f32_e32 v4, v5, v4
	s_mov_b32 s0, 0xda24260
	v_max3_f32 v3, v3, v4, s0
	s_mov_b64 s[0:1], exec
	v_readlane_b32 s10, v254, 21
	v_readlane_b32 s11, v254, 22
	s_and_b64 s[10:11], s[0:1], s[10:11]
	s_mov_b64 exec, s[10:11]
	v_mul_f32_e32 v4, 0x3b888889, v3
	v_mov_b32_e32 v5, s93
	ds_write_b32 v5, v4 offset:14336
	s_or_b64 exec, exec, s[0:1]
	s_mov_b32 s10, 0x43700000
	v_div_scale_f32 v4, s[0:1], v3, v3, s10
	v_rcp_f32_e32 v5, v4
	s_mov_b32 s0, 0x7020c0c
	v_fma_f32 v6, -v4, v5, 1.0
	v_fmac_f32_e32 v5, v6, v5
	v_div_scale_f32 v6, vcc, s10, v3, s10
	v_mul_f32_e32 v7, v6, v5
	v_fma_f32 v8, -v4, v7, v6
	v_fmac_f32_e32 v7, v8, v5
	v_fma_f32 v4, -v4, v7, v6
	v_div_fmas_f32 v4, v4, v5, v7
	v_div_fixup_f32 v3, v4, v3, s10
	v_mul_f32_e32 v4, v3, v1
	v_mul_f32_e32 v5, v3, v2
	v_mov_b32_e32 v6, v155
	v_cvt_pk_fp8_f32 v6, v4, v5
	v_cvt_pk_f32_fp8_e32 v[4:5], v6
	v_fma_f32 v1, v3, v1, -v4
	v_fma_f32 v2, v3, v2, -v5
	v_mov_b32_e32 v4, v155
	v_cvt_pk_fp8_f32 v4, v1, v2
	ds_read2st64_b32 v[2:3], v178 offset1:1
	v_lshlrev_b32_e32 v1, 16, v6
	v_and_b32_e32 v1, 0xff0000, v1
	v_lshlrev_b32_e32 v5, 24, v4
	v_lshlrev_b32_e32 v4, 16, v4
	s_waitcnt lgkmcnt(0)
	v_or3_b32 v1, v2, v1, v5
	v_lshlrev_b32_e32 v2, 8, v6
	v_perm_b32 v2, v4, v2, s0
	v_or_b32_e32 v2, v2, v3
	ds_write2st64_b32 v178, v1, v2 offset0:2 offset1:3
	ds_read2st64_b32 v[2:3], v178 offset0:8 offset1:9
	ds_read2st64_b32 v[4:5], v178 offset0:10 offset1:11
	s_mov_b32 s0, 0x3e6d3388
	s_waitcnt lgkmcnt(0)
	v_fma_f32 v1, |v4|, s0, 1.0
	v_rcp_f32_e32 v1, v1
	v_cmp_gt_f32_e32 vcc, 0, v4
	v_fmamk_f32 v6, v1, 0x3f07dc22, v210
	v_fmaak_f32 v6, v1, v6, 0x3f35f0e3
	v_fmaak_f32 v6, v1, v6, 0xbe11a98e
	v_fmaak_f32 v6, v1, v6, 0x3e027906
	v_mul_f32_e32 v1, v1, v6
	v_mul_f32_e32 v6, v4, v4
	v_mul_f32_e32 v6, 0xbf38aa3b, v6
	v_exp_f32_e32 v6, v6
	s_nop 0
	v_mul_f32_e32 v1, v6, v1
	v_mul_f32_e32 v6, v4, v1
	v_fma_f32 v1, -v4, v1, v4
	v_cndmask_b32_e32 v1, v1, v6, vcc
	v_mul_f32_e32 v1, v2, v1
	v_fma_f32 v2, |v5|, s0, 1.0
	v_rcp_f32_e32 v2, v2
	v_cmp_gt_f32_e32 vcc, 0, v5
	v_fmamk_f32 v4, v2, 0x3f07dc22, v210
	v_fmaak_f32 v4, v2, v4, 0x3f35f0e3
	v_fmaak_f32 v4, v2, v4, 0xbe11a98e
	v_fmaak_f32 v4, v2, v4, 0x3e027906
	v_mul_f32_e32 v2, v2, v4
	v_mul_f32_e32 v4, v5, v5
	v_mul_f32_e32 v4, 0xbf38aa3b, v4
	v_exp_f32_e32 v4, v4
	s_nop 0
	v_mul_f32_e32 v2, v4, v2
	v_mul_f32_e32 v4, v5, v2
	v_fma_f32 v2, -v5, v2, v5
	v_cndmask_b32_e32 v2, v2, v4, vcc
	v_mul_f32_e32 v2, v3, v2
	v_max_f32_e64 v3, |v1|, |v2|
	s_nop 1
	v_mov_b32_dpp v4, v3 quad_perm:[1,0,3,2] row_mask:0xf bank_mask:0xf bound_ctrl:1
	v_max_f32_e32 v4, v4, v4
	v_max_f32_e32 v3, v3, v4
	s_nop 1
	v_mov_b32_dpp v4, v3 quad_perm:[2,3,0,1] row_mask:0xf bank_mask:0xf bound_ctrl:1
	v_max_f32_e32 v4, v4, v4
	v_max_f32_e32 v3, v3, v4
	s_nop 1
	v_mov_b32_dpp v4, v3 row_half_mirror row_mask:0xf bank_mask:0xf bound_ctrl:1
	v_max_f32_e32 v4, v4, v4
	v_max_f32_e32 v3, v3, v4
	s_nop 1
	v_mov_b32_dpp v4, v3 row_mirror row_mask:0xf bank_mask:0xf bound_ctrl:1
	v_max_f32_e32 v4, v4, v4
	v_max_f32_e32 v3, v3, v4
	s_nop 0
	v_readlane_b32 s0, v3, 0
	v_readlane_b32 s1, v3, 16
	v_readlane_b32 s10, v3, 32
	v_readlane_b32 s11, v3, 48
	v_max_f32_e64 v3, s1, s1
	v_max_f32_e64 v4, s0, s0
	v_max_f32_e32 v3, v4, v3
	v_max_f32_e64 v4, s11, s11
	v_max_f32_e64 v5, s10, s10
	v_max_f32_e32 v4, v5, v4
	s_mov_b32 s0, 0xda24260
	v_max3_f32 v3, v3, v4, s0
	s_mov_b64 s[0:1], exec
	v_readlane_b32 s10, v254, 21
	v_readlane_b32 s11, v254, 22
	s_and_b64 s[10:11], s[0:1], s[10:11]
	s_mov_b64 exec, s[10:11]
	v_mul_f32_e32 v4, 0x3b888889, v3
	v_mov_b32_e32 v5, s93
	ds_write_b32 v5, v4 offset:14340
	s_or_b64 exec, exec, s[0:1]
	s_mov_b32 s10, 0x43700000
	v_div_scale_f32 v4, s[0:1], v3, v3, s10
	v_rcp_f32_e32 v5, v4
	s_mov_b32 s0, 0x7020c0c
	v_fma_f32 v6, -v4, v5, 1.0
	v_fmac_f32_e32 v5, v6, v5
	v_div_scale_f32 v6, vcc, s10, v3, s10
	v_mul_f32_e32 v7, v6, v5
	v_fma_f32 v8, -v4, v7, v6
	v_fmac_f32_e32 v7, v8, v5
	v_fma_f32 v4, -v4, v7, v6
	v_div_fmas_f32 v4, v4, v5, v7
	v_div_fixup_f32 v3, v4, v3, s10
	v_mul_f32_e32 v4, v3, v1
	v_mul_f32_e32 v5, v3, v2
	v_mov_b32_e32 v6, v155
	v_cvt_pk_fp8_f32 v6, v4, v5
	v_cvt_pk_f32_fp8_e32 v[4:5], v6
	v_fma_f32 v1, v3, v1, -v4
	v_fma_f32 v2, v3, v2, -v5
	v_mov_b32_e32 v4, v155
	v_cvt_pk_fp8_f32 v4, v1, v2
	ds_read2st64_b32 v[2:3], v178 offset0:6 offset1:7
	v_lshlrev_b32_e32 v1, 16, v6
	v_and_b32_e32 v1, 0xff0000, v1
	v_lshlrev_b32_e32 v5, 24, v4
	v_lshlrev_b32_e32 v4, 16, v4
	s_waitcnt lgkmcnt(0)
	v_or3_b32 v1, v2, v1, v5
	v_lshlrev_b32_e32 v2, 8, v6
	v_perm_b32 v2, v4, v2, s0
	v_or_b32_e32 v2, v2, v3
	ds_write2st64_b32 v178, v1, v2 offset0:8 offset1:9
	ds_read2st64_b32 v[2:3], v178 offset0:14 offset1:15
	ds_read2st64_b32 v[4:5], v178 offset0:16 offset1:17
	s_mov_b32 s0, 0x3e6d3388
	s_waitcnt lgkmcnt(0)
	v_fma_f32 v1, |v4|, s0, 1.0
	v_rcp_f32_e32 v1, v1
	v_cmp_gt_f32_e32 vcc, 0, v4
	v_fmamk_f32 v6, v1, 0x3f07dc22, v210
	v_fmaak_f32 v6, v1, v6, 0x3f35f0e3
	v_fmaak_f32 v6, v1, v6, 0xbe11a98e
	v_fmaak_f32 v6, v1, v6, 0x3e027906
	v_mul_f32_e32 v1, v1, v6
	v_mul_f32_e32 v6, v4, v4
	v_mul_f32_e32 v6, 0xbf38aa3b, v6
	v_exp_f32_e32 v6, v6
	s_nop 0
	v_mul_f32_e32 v1, v6, v1
	v_mul_f32_e32 v6, v4, v1
	v_fma_f32 v1, -v4, v1, v4
	v_cndmask_b32_e32 v1, v1, v6, vcc
	v_mul_f32_e32 v1, v2, v1
	v_fma_f32 v2, |v5|, s0, 1.0
	v_rcp_f32_e32 v2, v2
	v_cmp_gt_f32_e32 vcc, 0, v5
	v_fmamk_f32 v4, v2, 0x3f07dc22, v210
	v_fmaak_f32 v4, v2, v4, 0x3f35f0e3
	v_fmaak_f32 v4, v2, v4, 0xbe11a98e
	v_fmaak_f32 v4, v2, v4, 0x3e027906
	v_mul_f32_e32 v2, v2, v4
	v_mul_f32_e32 v4, v5, v5
	v_mul_f32_e32 v4, 0xbf38aa3b, v4
	v_exp_f32_e32 v4, v4
	s_nop 0
	v_mul_f32_e32 v2, v4, v2
	v_mul_f32_e32 v4, v5, v2
	v_fma_f32 v2, -v5, v2, v5
	v_cndmask_b32_e32 v2, v2, v4, vcc
	v_mul_f32_e32 v2, v3, v2
	v_max_f32_e64 v3, |v1|, |v2|
	s_nop 1
	v_mov_b32_dpp v4, v3 quad_perm:[1,0,3,2] row_mask:0xf bank_mask:0xf bound_ctrl:1
	v_max_f32_e32 v4, v4, v4
	v_max_f32_e32 v3, v3, v4
	s_nop 1
	v_mov_b32_dpp v4, v3 quad_perm:[2,3,0,1] row_mask:0xf bank_mask:0xf bound_ctrl:1
	v_max_f32_e32 v4, v4, v4
	v_max_f32_e32 v3, v3, v4
	s_nop 1
	v_mov_b32_dpp v4, v3 row_half_mirror row_mask:0xf bank_mask:0xf bound_ctrl:1
	v_max_f32_e32 v4, v4, v4
	v_max_f32_e32 v3, v3, v4
	s_nop 1
	v_mov_b32_dpp v4, v3 row_mirror row_mask:0xf bank_mask:0xf bound_ctrl:1
	v_max_f32_e32 v4, v4, v4
	v_max_f32_e32 v3, v3, v4
	s_nop 0
	v_readlane_b32 s0, v3, 0
	v_readlane_b32 s1, v3, 16
	v_readlane_b32 s10, v3, 32
	v_readlane_b32 s11, v3, 48
	v_max_f32_e64 v3, s1, s1
	v_max_f32_e64 v4, s0, s0
	v_max_f32_e32 v3, v4, v3
	v_max_f32_e64 v4, s11, s11
	v_max_f32_e64 v5, s10, s10
	v_max_f32_e32 v4, v5, v4
	s_mov_b32 s0, 0xda24260
	v_max3_f32 v3, v3, v4, s0
	s_mov_b64 s[0:1], exec
	v_readlane_b32 s10, v254, 21
	v_readlane_b32 s11, v254, 22
	s_and_b64 s[10:11], s[0:1], s[10:11]
	s_mov_b64 exec, s[10:11]
	v_mul_f32_e32 v4, 0x3b888889, v3
	v_mov_b32_e32 v5, s93
	ds_write_b32 v5, v4 offset:14344
	s_or_b64 exec, exec, s[0:1]
	s_mov_b32 s10, 0x43700000
	v_div_scale_f32 v4, s[0:1], v3, v3, s10
	v_rcp_f32_e32 v5, v4
	s_mov_b32 s0, 0x7020c0c
	v_fma_f32 v6, -v4, v5, 1.0
	v_fmac_f32_e32 v5, v6, v5
	v_div_scale_f32 v6, vcc, s10, v3, s10
	v_mul_f32_e32 v7, v6, v5
	v_fma_f32 v8, -v4, v7, v6
	v_fmac_f32_e32 v7, v8, v5
	v_fma_f32 v4, -v4, v7, v6
	v_div_fmas_f32 v4, v4, v5, v7
	v_div_fixup_f32 v3, v4, v3, s10
	v_mul_f32_e32 v4, v3, v1
	v_mul_f32_e32 v5, v3, v2
	v_mov_b32_e32 v6, v155
	v_cvt_pk_fp8_f32 v6, v4, v5
	v_cvt_pk_f32_fp8_e32 v[4:5], v6
	v_fma_f32 v1, v3, v1, -v4
	v_fma_f32 v2, v3, v2, -v5
	v_mov_b32_e32 v4, v155
	v_cvt_pk_fp8_f32 v4, v1, v2
	ds_read2st64_b32 v[2:3], v178 offset0:12 offset1:13
	v_lshlrev_b32_e32 v1, 16, v6
	v_and_b32_e32 v1, 0xff0000, v1
	v_lshlrev_b32_e32 v5, 24, v4
	v_lshlrev_b32_e32 v4, 16, v4
	s_waitcnt lgkmcnt(0)
	v_or3_b32 v1, v2, v1, v5
	v_lshlrev_b32_e32 v2, 8, v6
	v_perm_b32 v2, v4, v2, s0
	v_or_b32_e32 v2, v2, v3
	ds_write2st64_b32 v178, v1, v2 offset0:14 offset1:15
	ds_read2st64_b32 v[2:3], v178 offset0:20 offset1:21
	ds_read2st64_b32 v[4:5], v178 offset0:22 offset1:23
	s_mov_b32 s0, 0x3e6d3388
	s_waitcnt lgkmcnt(0)
	v_fma_f32 v1, |v4|, s0, 1.0
	v_rcp_f32_e32 v1, v1
	v_cmp_gt_f32_e32 vcc, 0, v4
	v_fmamk_f32 v6, v1, 0x3f07dc22, v210
	v_fmaak_f32 v6, v1, v6, 0x3f35f0e3
	v_fmaak_f32 v6, v1, v6, 0xbe11a98e
	v_fmaak_f32 v6, v1, v6, 0x3e027906
	v_mul_f32_e32 v1, v1, v6
	v_mul_f32_e32 v6, v4, v4
	v_mul_f32_e32 v6, 0xbf38aa3b, v6
	v_exp_f32_e32 v6, v6
	s_nop 0
	v_mul_f32_e32 v1, v6, v1
	v_mul_f32_e32 v6, v4, v1
	v_fma_f32 v1, -v4, v1, v4
	v_cndmask_b32_e32 v1, v1, v6, vcc
	v_mul_f32_e32 v1, v2, v1
	v_fma_f32 v2, |v5|, s0, 1.0
	v_rcp_f32_e32 v2, v2
	v_cmp_gt_f32_e32 vcc, 0, v5
	v_fmamk_f32 v4, v2, 0x3f07dc22, v210
	v_fmaak_f32 v4, v2, v4, 0x3f35f0e3
	v_fmaak_f32 v4, v2, v4, 0xbe11a98e
	v_fmaak_f32 v4, v2, v4, 0x3e027906
	v_mul_f32_e32 v2, v2, v4
	v_mul_f32_e32 v4, v5, v5
	v_mul_f32_e32 v4, 0xbf38aa3b, v4
	v_exp_f32_e32 v4, v4
	s_nop 0
	v_mul_f32_e32 v2, v4, v2
	v_mul_f32_e32 v4, v5, v2
	v_fma_f32 v2, -v5, v2, v5
	v_cndmask_b32_e32 v2, v2, v4, vcc
	v_mul_f32_e32 v2, v3, v2
	v_max_f32_e64 v3, |v1|, |v2|
	s_nop 1
	v_mov_b32_dpp v4, v3 quad_perm:[1,0,3,2] row_mask:0xf bank_mask:0xf bound_ctrl:1
	v_max_f32_e32 v4, v4, v4
	v_max_f32_e32 v3, v3, v4
	s_nop 1
	v_mov_b32_dpp v4, v3 quad_perm:[2,3,0,1] row_mask:0xf bank_mask:0xf bound_ctrl:1
	v_max_f32_e32 v4, v4, v4
	v_max_f32_e32 v3, v3, v4
	s_nop 1
	v_mov_b32_dpp v4, v3 row_half_mirror row_mask:0xf bank_mask:0xf bound_ctrl:1
	v_max_f32_e32 v4, v4, v4
	v_max_f32_e32 v3, v3, v4
	s_nop 1
	v_mov_b32_dpp v4, v3 row_mirror row_mask:0xf bank_mask:0xf bound_ctrl:1
	v_max_f32_e32 v4, v4, v4
	v_max_f32_e32 v3, v3, v4
	s_nop 0
	v_readlane_b32 s0, v3, 0
	v_readlane_b32 s1, v3, 16
	v_readlane_b32 s10, v3, 32
	v_readlane_b32 s11, v3, 48
	v_max_f32_e64 v3, s1, s1
	v_max_f32_e64 v4, s0, s0
	v_max_f32_e32 v3, v4, v3
	v_max_f32_e64 v4, s11, s11
	v_max_f32_e64 v5, s10, s10
	v_max_f32_e32 v4, v5, v4
	s_mov_b32 s0, 0xda24260
	v_max3_f32 v3, v3, v4, s0
	s_mov_b64 s[0:1], exec
	v_readlane_b32 s10, v254, 21
	v_readlane_b32 s11, v254, 22
	s_and_b64 s[10:11], s[0:1], s[10:11]
	s_mov_b64 exec, s[10:11]
	v_mul_f32_e32 v4, 0x3b888889, v3
	v_mov_b32_e32 v5, s93
	ds_write_b32 v5, v4 offset:14348
	s_or_b64 exec, exec, s[0:1]
	s_mov_b32 s10, 0x43700000
	v_div_scale_f32 v4, s[0:1], v3, v3, s10
	v_rcp_f32_e32 v5, v4
	s_mov_b32 s0, 0x7020c0c
	v_fma_f32 v6, -v4, v5, 1.0
	v_fmac_f32_e32 v5, v6, v5
	v_div_scale_f32 v6, vcc, s10, v3, s10
	v_mul_f32_e32 v7, v6, v5
	v_fma_f32 v8, -v4, v7, v6
	v_fmac_f32_e32 v7, v8, v5
	v_fma_f32 v4, -v4, v7, v6
	v_div_fmas_f32 v4, v4, v5, v7
	v_div_fixup_f32 v3, v4, v3, s10
	v_mul_f32_e32 v4, v3, v1
	v_mul_f32_e32 v5, v3, v2
	v_mov_b32_e32 v6, v155
	v_cvt_pk_fp8_f32 v6, v4, v5
	v_cvt_pk_f32_fp8_e32 v[4:5], v6
	v_fma_f32 v1, v3, v1, -v4
	v_fma_f32 v2, v3, v2, -v5
	v_mov_b32_e32 v4, v155
	v_cvt_pk_fp8_f32 v4, v1, v2
	ds_read2st64_b32 v[2:3], v178 offset0:18 offset1:19
	v_lshlrev_b32_e32 v1, 16, v6
	v_and_b32_e32 v1, 0xff0000, v1
	v_lshlrev_b32_e32 v5, 24, v4
	v_lshlrev_b32_e32 v4, 16, v4
	s_waitcnt lgkmcnt(0)
	v_or3_b32 v1, v2, v1, v5
	v_lshlrev_b32_e32 v2, 8, v6
	v_perm_b32 v2, v4, v2, s0
	v_or_b32_e32 v2, v2, v3
	ds_write2st64_b32 v178, v1, v2 offset0:20 offset1:21
	ds_read2st64_b32 v[2:3], v178 offset0:26 offset1:27
	ds_read2st64_b32 v[4:5], v178 offset0:28 offset1:29
	s_mov_b32 s0, 0x3e6d3388
	s_waitcnt lgkmcnt(0)
	v_fma_f32 v1, |v4|, s0, 1.0
	v_rcp_f32_e32 v1, v1
	v_cmp_gt_f32_e32 vcc, 0, v4
	v_fmamk_f32 v6, v1, 0x3f07dc22, v210
	v_fmaak_f32 v6, v1, v6, 0x3f35f0e3
	v_fmaak_f32 v6, v1, v6, 0xbe11a98e
	v_fmaak_f32 v6, v1, v6, 0x3e027906
	v_mul_f32_e32 v1, v1, v6
	v_mul_f32_e32 v6, v4, v4
	v_mul_f32_e32 v6, 0xbf38aa3b, v6
	v_exp_f32_e32 v6, v6
	s_nop 0
	v_mul_f32_e32 v1, v6, v1
	v_mul_f32_e32 v6, v4, v1
	v_fma_f32 v1, -v4, v1, v4
	v_cndmask_b32_e32 v1, v1, v6, vcc
	v_mul_f32_e32 v1, v2, v1
	v_fma_f32 v2, |v5|, s0, 1.0
	v_rcp_f32_e32 v2, v2
	v_cmp_gt_f32_e32 vcc, 0, v5
	v_fmamk_f32 v4, v2, 0x3f07dc22, v210
	v_fmaak_f32 v4, v2, v4, 0x3f35f0e3
	v_fmaak_f32 v4, v2, v4, 0xbe11a98e
	v_fmaak_f32 v4, v2, v4, 0x3e027906
	v_mul_f32_e32 v2, v2, v4
	v_mul_f32_e32 v4, v5, v5
	v_mul_f32_e32 v4, 0xbf38aa3b, v4
	v_exp_f32_e32 v4, v4
	s_nop 0
	v_mul_f32_e32 v2, v4, v2
	v_mul_f32_e32 v4, v5, v2
	v_fma_f32 v2, -v5, v2, v5
	v_cndmask_b32_e32 v2, v2, v4, vcc
	v_mul_f32_e32 v2, v3, v2
	v_max_f32_e64 v3, |v1|, |v2|
	s_nop 1
	v_mov_b32_dpp v4, v3 quad_perm:[1,0,3,2] row_mask:0xf bank_mask:0xf bound_ctrl:1
	v_max_f32_e32 v4, v4, v4
	v_max_f32_e32 v3, v3, v4
	s_nop 1
	v_mov_b32_dpp v4, v3 quad_perm:[2,3,0,1] row_mask:0xf bank_mask:0xf bound_ctrl:1
	v_max_f32_e32 v4, v4, v4
	v_max_f32_e32 v3, v3, v4
	s_nop 1
	v_mov_b32_dpp v4, v3 row_half_mirror row_mask:0xf bank_mask:0xf bound_ctrl:1
	v_max_f32_e32 v4, v4, v4
	v_max_f32_e32 v3, v3, v4
	s_nop 1
	v_mov_b32_dpp v4, v3 row_mirror row_mask:0xf bank_mask:0xf bound_ctrl:1
	v_max_f32_e32 v4, v4, v4
	v_max_f32_e32 v3, v3, v4
	s_nop 0
	v_readlane_b32 s0, v3, 0
	v_readlane_b32 s1, v3, 16
	v_readlane_b32 s10, v3, 32
	v_readlane_b32 s11, v3, 48
	v_max_f32_e64 v3, s1, s1
	v_max_f32_e64 v4, s0, s0
	v_max_f32_e32 v3, v4, v3
	v_max_f32_e64 v4, s11, s11
	v_max_f32_e64 v5, s10, s10
	v_max_f32_e32 v4, v5, v4
	s_mov_b32 s0, 0xda24260
	v_max3_f32 v3, v3, v4, s0
	s_mov_b64 s[0:1], exec
	v_readlane_b32 s10, v254, 21
	v_readlane_b32 s11, v254, 22
	s_and_b64 s[10:11], s[0:1], s[10:11]
	s_mov_b64 exec, s[10:11]
	v_mul_f32_e32 v4, 0x3b888889, v3
	v_mov_b32_e32 v5, s93
	ds_write_b32 v5, v4 offset:14352
	s_or_b64 exec, exec, s[0:1]
	s_mov_b32 s10, 0x43700000
	v_div_scale_f32 v4, s[0:1], v3, v3, s10
	v_rcp_f32_e32 v5, v4
	s_mov_b32 s0, 0x7020c0c
	v_fma_f32 v6, -v4, v5, 1.0
	v_fmac_f32_e32 v5, v6, v5
	v_div_scale_f32 v6, vcc, s10, v3, s10
	v_mul_f32_e32 v7, v6, v5
	v_fma_f32 v8, -v4, v7, v6
	v_fmac_f32_e32 v7, v8, v5
	v_fma_f32 v4, -v4, v7, v6
	v_div_fmas_f32 v4, v4, v5, v7
	v_div_fixup_f32 v3, v4, v3, s10
	v_mul_f32_e32 v4, v3, v1
	v_mul_f32_e32 v5, v3, v2
	v_mov_b32_e32 v6, v155
	v_cvt_pk_fp8_f32 v6, v4, v5
	v_cvt_pk_f32_fp8_e32 v[4:5], v6
	v_fma_f32 v1, v3, v1, -v4
	v_fma_f32 v2, v3, v2, -v5
	v_mov_b32_e32 v4, v155
	v_cvt_pk_fp8_f32 v4, v1, v2
	ds_read2st64_b32 v[2:3], v178 offset0:24 offset1:25
	v_lshlrev_b32_e32 v1, 16, v6
	v_and_b32_e32 v1, 0xff0000, v1
	v_lshlrev_b32_e32 v5, 24, v4
	v_lshlrev_b32_e32 v4, 16, v4
	s_waitcnt lgkmcnt(0)
	v_or3_b32 v1, v2, v1, v5
	v_lshlrev_b32_e32 v2, 8, v6
	v_perm_b32 v2, v4, v2, s0
	v_or_b32_e32 v2, v2, v3
	ds_write2st64_b32 v178, v1, v2 offset0:26 offset1:27
	ds_read2st64_b32 v[2:3], v178 offset0:32 offset1:33
	ds_read2st64_b32 v[4:5], v178 offset0:34 offset1:35
	s_mov_b32 s0, 0x3e6d3388
	s_waitcnt lgkmcnt(0)
	v_fma_f32 v1, |v4|, s0, 1.0
	v_rcp_f32_e32 v1, v1
	v_cmp_gt_f32_e32 vcc, 0, v4
	v_fmamk_f32 v6, v1, 0x3f07dc22, v210
	v_fmaak_f32 v6, v1, v6, 0x3f35f0e3
	v_fmaak_f32 v6, v1, v6, 0xbe11a98e
	v_fmaak_f32 v6, v1, v6, 0x3e027906
	v_mul_f32_e32 v1, v1, v6
	v_mul_f32_e32 v6, v4, v4
	v_mul_f32_e32 v6, 0xbf38aa3b, v6
	v_exp_f32_e32 v6, v6
	s_nop 0
	v_mul_f32_e32 v1, v6, v1
	v_mul_f32_e32 v6, v4, v1
	v_fma_f32 v1, -v4, v1, v4
	v_cndmask_b32_e32 v1, v1, v6, vcc
	v_mul_f32_e32 v1, v2, v1
	v_fma_f32 v2, |v5|, s0, 1.0
	v_rcp_f32_e32 v2, v2
	v_cmp_gt_f32_e32 vcc, 0, v5
	v_fmamk_f32 v4, v2, 0x3f07dc22, v210
	v_fmaak_f32 v4, v2, v4, 0x3f35f0e3
	v_fmaak_f32 v4, v2, v4, 0xbe11a98e
	v_fmaak_f32 v4, v2, v4, 0x3e027906
	v_mul_f32_e32 v2, v2, v4
	v_mul_f32_e32 v4, v5, v5
	v_mul_f32_e32 v4, 0xbf38aa3b, v4
	v_exp_f32_e32 v4, v4
	s_nop 0
	v_mul_f32_e32 v2, v4, v2
	v_mul_f32_e32 v4, v5, v2
	v_fma_f32 v2, -v5, v2, v5
	v_cndmask_b32_e32 v2, v2, v4, vcc
	v_mul_f32_e32 v2, v3, v2
	v_max_f32_e64 v3, |v1|, |v2|
	s_nop 1
	v_mov_b32_dpp v4, v3 quad_perm:[1,0,3,2] row_mask:0xf bank_mask:0xf bound_ctrl:1
	v_max_f32_e32 v4, v4, v4
	v_max_f32_e32 v3, v3, v4
	s_nop 1
	v_mov_b32_dpp v4, v3 quad_perm:[2,3,0,1] row_mask:0xf bank_mask:0xf bound_ctrl:1
	v_max_f32_e32 v4, v4, v4
	v_max_f32_e32 v3, v3, v4
	s_nop 1
	v_mov_b32_dpp v4, v3 row_half_mirror row_mask:0xf bank_mask:0xf bound_ctrl:1
	v_max_f32_e32 v4, v4, v4
	v_max_f32_e32 v3, v3, v4
	s_nop 1
	v_mov_b32_dpp v4, v3 row_mirror row_mask:0xf bank_mask:0xf bound_ctrl:1
	v_max_f32_e32 v4, v4, v4
	v_max_f32_e32 v3, v3, v4
	s_nop 0
	v_readlane_b32 s0, v3, 0
	v_readlane_b32 s1, v3, 16
	v_readlane_b32 s10, v3, 32
	v_readlane_b32 s11, v3, 48
	v_max_f32_e64 v3, s1, s1
	v_max_f32_e64 v4, s0, s0
	v_max_f32_e32 v3, v4, v3
	v_max_f32_e64 v4, s11, s11
	v_max_f32_e64 v5, s10, s10
	v_max_f32_e32 v4, v5, v4
	s_mov_b32 s0, 0xda24260
	v_max3_f32 v3, v3, v4, s0
	s_mov_b64 s[0:1], exec
	v_readlane_b32 s10, v254, 21
	v_readlane_b32 s11, v254, 22
	s_and_b64 s[10:11], s[0:1], s[10:11]
	s_mov_b64 exec, s[10:11]
	v_mul_f32_e32 v4, 0x3b888889, v3
	v_mov_b32_e32 v5, s93
	ds_write_b32 v5, v4 offset:14356
	s_or_b64 exec, exec, s[0:1]
	s_mov_b32 s10, 0x43700000
	v_div_scale_f32 v4, s[0:1], v3, v3, s10
	v_rcp_f32_e32 v5, v4
	s_mov_b32 s0, 0x7020c0c
	v_fma_f32 v6, -v4, v5, 1.0
	v_fmac_f32_e32 v5, v6, v5
	v_div_scale_f32 v6, vcc, s10, v3, s10
	v_mul_f32_e32 v7, v6, v5
	v_fma_f32 v8, -v4, v7, v6
	v_fmac_f32_e32 v7, v8, v5
	v_fma_f32 v4, -v4, v7, v6
	v_div_fmas_f32 v4, v4, v5, v7
	v_div_fixup_f32 v3, v4, v3, s10
	v_mul_f32_e32 v4, v3, v1
	v_mul_f32_e32 v5, v3, v2
	v_mov_b32_e32 v6, v155
	v_cvt_pk_fp8_f32 v6, v4, v5
	v_cvt_pk_f32_fp8_e32 v[4:5], v6
	v_fma_f32 v1, v3, v1, -v4
	v_fma_f32 v2, v3, v2, -v5
	v_mov_b32_e32 v4, v155
	v_cvt_pk_fp8_f32 v4, v1, v2
	ds_read2st64_b32 v[2:3], v178 offset0:30 offset1:31
	v_lshlrev_b32_e32 v1, 16, v6
	v_and_b32_e32 v1, 0xff0000, v1
	v_lshlrev_b32_e32 v5, 24, v4
	v_lshlrev_b32_e32 v4, 16, v4
	s_waitcnt lgkmcnt(0)
	v_or3_b32 v1, v2, v1, v5
	v_lshlrev_b32_e32 v2, 8, v6
	v_perm_b32 v2, v4, v2, s0
	v_or_b32_e32 v2, v2, v3
	ds_write2st64_b32 v178, v1, v2 offset0:32 offset1:33
	ds_read2st64_b32 v[2:3], v178 offset0:38 offset1:39
	ds_read2st64_b32 v[4:5], v178 offset0:40 offset1:41
	s_mov_b32 s0, 0x3e6d3388
	s_waitcnt lgkmcnt(0)
	v_fma_f32 v1, |v4|, s0, 1.0
	v_rcp_f32_e32 v1, v1
	v_cmp_gt_f32_e32 vcc, 0, v4
	v_fmamk_f32 v6, v1, 0x3f07dc22, v210
	v_fmaak_f32 v6, v1, v6, 0x3f35f0e3
	v_fmaak_f32 v6, v1, v6, 0xbe11a98e
	v_fmaak_f32 v6, v1, v6, 0x3e027906
	v_mul_f32_e32 v1, v1, v6
	v_mul_f32_e32 v6, v4, v4
	v_mul_f32_e32 v6, 0xbf38aa3b, v6
	v_exp_f32_e32 v6, v6
	s_nop 0
	v_mul_f32_e32 v1, v6, v1
	v_mul_f32_e32 v6, v4, v1
	v_fma_f32 v1, -v4, v1, v4
	v_cndmask_b32_e32 v1, v1, v6, vcc
	v_mul_f32_e32 v1, v2, v1
	v_fma_f32 v2, |v5|, s0, 1.0
	v_rcp_f32_e32 v2, v2
	v_cmp_gt_f32_e32 vcc, 0, v5
	v_fmamk_f32 v4, v2, 0x3f07dc22, v210
	v_fmaak_f32 v4, v2, v4, 0x3f35f0e3
	v_fmaak_f32 v4, v2, v4, 0xbe11a98e
	v_fmaak_f32 v4, v2, v4, 0x3e027906
	v_mul_f32_e32 v2, v2, v4
	v_mul_f32_e32 v4, v5, v5
	v_mul_f32_e32 v4, 0xbf38aa3b, v4
	v_exp_f32_e32 v4, v4
	s_nop 0
	v_mul_f32_e32 v2, v4, v2
	v_mul_f32_e32 v4, v5, v2
	v_fma_f32 v2, -v5, v2, v5
	v_cndmask_b32_e32 v2, v2, v4, vcc
	v_mul_f32_e32 v2, v3, v2
	v_max_f32_e64 v3, |v1|, |v2|
	s_nop 1
	v_mov_b32_dpp v4, v3 quad_perm:[1,0,3,2] row_mask:0xf bank_mask:0xf bound_ctrl:1
	v_max_f32_e32 v4, v4, v4
	v_max_f32_e32 v3, v3, v4
	s_nop 1
	v_mov_b32_dpp v4, v3 quad_perm:[2,3,0,1] row_mask:0xf bank_mask:0xf bound_ctrl:1
	v_max_f32_e32 v4, v4, v4
	v_max_f32_e32 v3, v3, v4
	s_nop 1
	v_mov_b32_dpp v4, v3 row_half_mirror row_mask:0xf bank_mask:0xf bound_ctrl:1
	v_max_f32_e32 v4, v4, v4
	v_max_f32_e32 v3, v3, v4
	s_nop 1
	v_mov_b32_dpp v4, v3 row_mirror row_mask:0xf bank_mask:0xf bound_ctrl:1
	v_max_f32_e32 v4, v4, v4
	v_max_f32_e32 v3, v3, v4
	s_nop 0
	v_readlane_b32 s0, v3, 0
	v_readlane_b32 s1, v3, 16
	v_readlane_b32 s10, v3, 32
	v_readlane_b32 s11, v3, 48
	v_max_f32_e64 v3, s1, s1
	v_max_f32_e64 v4, s0, s0
	v_max_f32_e32 v3, v4, v3
	v_max_f32_e64 v4, s11, s11
	v_max_f32_e64 v5, s10, s10
	v_max_f32_e32 v4, v5, v4
	s_mov_b32 s0, 0xda24260
	v_max3_f32 v3, v3, v4, s0
	s_mov_b64 s[0:1], exec
	v_readlane_b32 s10, v254, 21
	v_readlane_b32 s11, v254, 22
	s_and_b64 s[10:11], s[0:1], s[10:11]
	s_mov_b64 exec, s[10:11]
	v_mul_f32_e32 v4, 0x3b888889, v3
	v_mov_b32_e32 v5, s93
	ds_write_b32 v5, v4 offset:14360
	s_or_b64 exec, exec, s[0:1]
	s_mov_b32 s10, 0x43700000
	v_div_scale_f32 v4, s[0:1], v3, v3, s10
	v_rcp_f32_e32 v5, v4
	s_mov_b32 s0, 0x7020c0c
	v_fma_f32 v6, -v4, v5, 1.0
	v_fmac_f32_e32 v5, v6, v5
	v_div_scale_f32 v6, vcc, s10, v3, s10
	v_mul_f32_e32 v7, v6, v5
	v_fma_f32 v8, -v4, v7, v6
	v_fmac_f32_e32 v7, v8, v5
	v_fma_f32 v4, -v4, v7, v6
	v_div_fmas_f32 v4, v4, v5, v7
	v_div_fixup_f32 v3, v4, v3, s10
	v_mul_f32_e32 v4, v3, v1
	v_mul_f32_e32 v5, v3, v2
	v_mov_b32_e32 v6, v155
	v_cvt_pk_fp8_f32 v6, v4, v5
	v_cvt_pk_f32_fp8_e32 v[4:5], v6
	v_fma_f32 v1, v3, v1, -v4
	v_fma_f32 v2, v3, v2, -v5
	v_mov_b32_e32 v4, v155
	v_cvt_pk_fp8_f32 v4, v1, v2
	ds_read2st64_b32 v[2:3], v178 offset0:36 offset1:37
	v_lshlrev_b32_e32 v1, 16, v6
	v_and_b32_e32 v1, 0xff0000, v1
	v_lshlrev_b32_e32 v5, 24, v4
	v_lshlrev_b32_e32 v4, 16, v4
	s_waitcnt lgkmcnt(0)
	v_or3_b32 v1, v2, v1, v5
	v_lshlrev_b32_e32 v2, 8, v6
	v_perm_b32 v2, v4, v2, s0
	v_or_b32_e32 v2, v2, v3
	ds_write2st64_b32 v178, v1, v2 offset0:38 offset1:39
	ds_read2st64_b32 v[2:3], v178 offset0:44 offset1:45
	ds_read2st64_b32 v[4:5], v178 offset0:46 offset1:47
	s_mov_b32 s0, 0x3e6d3388
	s_waitcnt lgkmcnt(0)
	v_fma_f32 v1, |v4|, s0, 1.0
	v_rcp_f32_e32 v1, v1
	v_cmp_gt_f32_e32 vcc, 0, v4
	v_fmamk_f32 v6, v1, 0x3f07dc22, v210
	v_fmaak_f32 v6, v1, v6, 0x3f35f0e3
	v_fmaak_f32 v6, v1, v6, 0xbe11a98e
	v_fmaak_f32 v6, v1, v6, 0x3e027906
	v_mul_f32_e32 v1, v1, v6
	v_mul_f32_e32 v6, v4, v4
	v_mul_f32_e32 v6, 0xbf38aa3b, v6
	v_exp_f32_e32 v6, v6
	s_nop 0
	v_mul_f32_e32 v1, v6, v1
	v_mul_f32_e32 v6, v4, v1
	v_fma_f32 v1, -v4, v1, v4
	v_cndmask_b32_e32 v1, v1, v6, vcc
	v_mul_f32_e32 v1, v2, v1
	v_fma_f32 v2, |v5|, s0, 1.0
	v_rcp_f32_e32 v2, v2
	v_cmp_gt_f32_e32 vcc, 0, v5
	v_fmamk_f32 v4, v2, 0x3f07dc22, v210
	v_fmaak_f32 v4, v2, v4, 0x3f35f0e3
	v_fmaak_f32 v4, v2, v4, 0xbe11a98e
	v_fmaak_f32 v4, v2, v4, 0x3e027906
	v_mul_f32_e32 v2, v2, v4
	v_mul_f32_e32 v4, v5, v5
	v_mul_f32_e32 v4, 0xbf38aa3b, v4
	v_exp_f32_e32 v4, v4
	s_nop 0
	v_mul_f32_e32 v2, v4, v2
	v_mul_f32_e32 v4, v5, v2
	v_fma_f32 v2, -v5, v2, v5
	v_cndmask_b32_e32 v2, v2, v4, vcc
	v_mul_f32_e32 v2, v3, v2
	v_max_f32_e64 v3, |v1|, |v2|
	s_nop 1
	v_mov_b32_dpp v4, v3 quad_perm:[1,0,3,2] row_mask:0xf bank_mask:0xf bound_ctrl:1
	v_max_f32_e32 v4, v4, v4
	v_max_f32_e32 v3, v3, v4
	s_nop 1
	v_mov_b32_dpp v4, v3 quad_perm:[2,3,0,1] row_mask:0xf bank_mask:0xf bound_ctrl:1
	v_max_f32_e32 v4, v4, v4
	v_max_f32_e32 v3, v3, v4
	s_nop 1
	v_mov_b32_dpp v4, v3 row_half_mirror row_mask:0xf bank_mask:0xf bound_ctrl:1
	v_max_f32_e32 v4, v4, v4
	v_max_f32_e32 v3, v3, v4
	s_nop 1
	v_mov_b32_dpp v4, v3 row_mirror row_mask:0xf bank_mask:0xf bound_ctrl:1
	v_max_f32_e32 v4, v4, v4
	v_max_f32_e32 v3, v3, v4
	s_nop 0
	v_readlane_b32 s0, v3, 0
	v_readlane_b32 s1, v3, 16
	v_readlane_b32 s10, v3, 32
	v_readlane_b32 s11, v3, 48
	v_max_f32_e64 v3, s1, s1
	v_max_f32_e64 v4, s0, s0
	v_max_f32_e32 v3, v4, v3
	v_max_f32_e64 v4, s11, s11
	v_max_f32_e64 v5, s10, s10
	v_max_f32_e32 v4, v5, v4
	s_mov_b32 s0, 0xda24260
	v_max3_f32 v3, v3, v4, s0
	s_mov_b64 s[0:1], exec
	v_readlane_b32 s10, v254, 21
	v_readlane_b32 s11, v254, 22
	s_and_b64 s[10:11], s[0:1], s[10:11]
	s_mov_b64 exec, s[10:11]
	v_mul_f32_e32 v4, 0x3b888889, v3
	v_mov_b32_e32 v5, s93
	ds_write_b32 v5, v4 offset:14364
	s_or_b64 exec, exec, s[0:1]
	s_mov_b32 s10, 0x43700000
	v_div_scale_f32 v4, s[0:1], v3, v3, s10
	v_rcp_f32_e32 v5, v4
	s_mov_b32 s0, 0x7020c0c
	v_readlane_b32 s12, v254, 29
	v_fma_f32 v6, -v4, v5, 1.0
	v_fmac_f32_e32 v5, v6, v5
	v_div_scale_f32 v6, vcc, s10, v3, s10
	v_mul_f32_e32 v7, v6, v5
	v_fma_f32 v8, -v4, v7, v6
	v_fmac_f32_e32 v7, v8, v5
	v_fma_f32 v4, -v4, v7, v6
	v_div_fmas_f32 v4, v4, v5, v7
	v_div_fixup_f32 v3, v4, v3, s10
	v_mul_f32_e32 v4, v3, v1
	v_mul_f32_e32 v5, v3, v2
	v_mov_b32_e32 v6, v155
	v_cvt_pk_fp8_f32 v6, v4, v5
	s_mov_b32 s10, 0
	v_cvt_pk_f32_fp8_e32 v[4:5], v6
	v_fma_f32 v1, v3, v1, -v4
	v_fma_f32 v2, v3, v2, -v5
	v_mov_b32_e32 v4, v155
	v_cvt_pk_fp8_f32 v4, v1, v2
	ds_read2st64_b32 v[2:3], v178 offset0:42 offset1:43
	v_lshlrev_b32_e32 v1, 16, v6
	v_and_b32_e32 v1, 0xff0000, v1
	v_lshlrev_b32_e32 v5, 24, v4
	v_lshlrev_b32_e32 v4, 16, v4
	s_waitcnt lgkmcnt(0)
	v_or3_b32 v1, v2, v1, v5
	v_lshlrev_b32_e32 v2, 8, v6
	v_perm_b32 v2, v4, v2, s0
	s_add_i32 s0, s40, 0xffffe000
	s_lshr_b32 s0, s0, 12
	s_add_i32 s0, s0, 1
	s_cmpk_gt_i32 s40, 0x1fff
	s_cselect_b32 s11, s0, 0
	v_readlane_b32 s0, v254, 20
	s_mul_i32 s0, s0, 3
	s_add_i32 s11, s11, s0
	v_or_b32_e32 v2, v2, v3
	s_mul_i32 s1, s11, 0x6000
	ds_write2st64_b32 v178, v1, v2 offset0:44 offset1:45
	s_mul_hi_u32 s0, s11, 0x6000
	s_add_u32 s1, s12, s1
	v_readlane_b32 s12, v254, 30
	s_waitcnt lgkmcnt(0)
	s_addc_u32 s12, s12, s0
	s_add_u32 s0, s1, 0x5000
	s_addc_u32 s1, s12, 0
